# GEMM K-loops: the two As[b0][0] LDS-DMA pieces of each K-tile pair moved from the 6-piece load segment (SP2) to the following 2-piece one (SP3); SP2 wait vmcnt 8->6: pieces per segment 2/4/4/6 instead
# baseline (speedup 1.0000x reference)
; #define PG8_STAGE(bufoff, gbase, voff) do { _Pragma("unroll") for (int _i = 0; _i < 2; ++_i) \
;         __builtin_amdgcn_global_load_lds((const unsigned*)((const char*)(gbase) + (voff)[_i]), (PG8_LAS unsigned*)(lds + (bufoff) + ldsw + _i * 8192), 16, 0, 0); } while (0)
; #define PG8_LDA(dst, b, h) do { _Pragma("unroll") for (int m = 0; m < 4; ++m) _Pragma("unroll") for (int k = 0; k < 2; ++k) dst[m][k] = *(const PG8_LAS bf16x8*)(lds + PG8_SA(b, h) + aoff + m * 2048 + k * 1024); } while (0)
; #define PG8_LDB(dst, b, h) do { _Pragma("unroll") for (int n = 0; n < 2; ++n) _Pragma("unroll") for (int k = 0; k < 2; ++k) dst[n][k] = *(const PG8_LAS bf16x8*)(lds + PG8_SB(b, h) + boff + n * 2048 + k * 1024); } while (0)
; #define PG8_MMA(ai, bj, At, Bt) do { __builtin_amdgcn_s_setprio(1); _Pragma("unroll") for (int m = 0; m < 4; ++m) _Pragma("unroll") for (int n = 0; n < 2; ++n) _Pragma("unroll") for (int k = 0; k < 2; ++k) \
;         acc[ai][bj][m][n] = __builtin_amdgcn_mfma_f32_16x16x32_bf16(Bt[n][k], At[m][k], acc[ai][bj][m][n], 0, 0, 0); __builtin_amdgcn_s_setprio(0); } while (0)
; #define PG8_WAIT_V(n) asm volatile("s_waitcnt vmcnt(" #n ")" ::: "memory")
; #define PG8_WAIT_L(n) asm volatile("s_waitcnt lgkmcnt(" #n ")" ::: "memory")
; template <class Epi, class Sched, bool ALIGN_EPI = false, bool SP2 = false>
; __device__ __forceinline__ void gemm_phase(PG8_LAS unsigned char* lds, const Gemm g, const Sched& S, const Epi& E) {
;     ...
;             const bool last = (t == nt - 2);
;             const char* a1 = cA + (size_t)(t + 1) * kstep;
;             const char* a2 = last ? nA : cA + (size_t)(t + 2) * kstep; const char* b2 = last ? nB : cB + (size_t)(t + 2) * kstep;
;             const char* a3 = a2 + kstep; const char* b3 = b2 + kstep;
;             if (last && has_next) S.a_ready(nxt);
;             if constexpr (SP2) {
;             PG8_LDB(B0, 0, 0); PG8_LDB(B1, 0, 1); PG8_SCHED; PG8_LDA(At, 0, 0); PG8_STAGE(PG8_SA(1, 1), a1 + hstep, voffA);
;             PG8_WAIT_V(8); PG8_WAIT_L(0); PG8_BAR; PG8_MMA(0, 0, At, B0); PG8_MMA(0, 1, At, B1); PG8_BAR; PG8_SCHED;
;             PG8_LDA(At, 0, 1); PG8_STAGE(PG8_SB(0, 0), b2, voffB); PG8_STAGE(PG8_SB(0, 1), b2 + hstep, voffB); PG8_STAGE(PG8_SA(0, 0), a2, voffA);
;             PG8_WAIT_V(8); PG8_WAIT_L(0); PG8_BAR; PG8_MMA(1, 0, At, B0); PG8_MMA(1, 1, At, B1); PG8_BAR; PG8_SCHED;
.LBB0_119:
	ds_read_b128 v[154:157], v151
	ds_read_b128 v[158:161], v151 offset:1024
	ds_read_b128 v[162:165], v151 offset:2048
	ds_read_b128 v[166:169], v151 offset:3072
	ds_read_b128 v[170:173], v152
	ds_read_b128 v[174:177], v152 offset:1024
	ds_read_b128 v[178:181], v152 offset:2048
	ds_read_b128 v[182:185], v152 offset:3072
	s_add_u32 s70, s68, 0xfff80080
	s_addc_u32 s71, s69, -1
	s_cmp_eq_u32 s93, 28
	s_cselect_b32 s73, s35, s71
	s_cselect_b32 s72, s89, s70
	s_cselect_b32 s71, s21, s92
	s_cselect_b32 s70, s90, s91
	v_lshl_add_u64 v[218:219], s[68:69], 0, v[136:137]
	s_add_i32 m0, s19, 0xc000
	ds_read_b128 v[186:189], v153
	ds_read_b128 v[190:193], v153 offset:1024
	ds_read_b128 v[194:197], v153 offset:2048
	ds_read_b128 v[198:201], v153 offset:3072
	ds_read_b128 v[202:205], v153 offset:4096
	ds_read_b128 v[206:209], v153 offset:5120
	ds_read_b128 v[210:213], v153 offset:6144
	ds_read_b128 v[214:217], v153 offset:7168
	global_load_lds_dwordx4 v[218:219], off
	v_lshl_add_u64 v[218:219], s[68:69], 0, v[138:139]
	s_add_i32 m0, s19, 0xe000
	s_nop 0
	global_load_lds_dwordx4 v[218:219], off
	s_waitcnt vmcnt(8)
	s_waitcnt lgkmcnt(0)
	s_barrier
	s_setprio 1
	s_waitcnt lgkmcnt(0)
	v_mfma_f32_16x16x32_bf16 v[124:127], v[154:157], v[186:189], v[124:127]
	v_mfma_f32_16x16x32_bf16 v[120:123], v[162:165], v[186:189], v[120:123]
	v_mfma_f32_16x16x32_bf16 v[116:119], v[154:157], v[194:197], v[116:119]
	v_mfma_f32_16x16x32_bf16 v[112:115], v[162:165], v[194:197], v[112:115]
	v_mfma_f32_16x16x32_bf16 v[100:103], v[154:157], v[202:205], v[100:103]
	v_mfma_f32_16x16x32_bf16 v[96:99], v[162:165], v[202:205], v[96:99]
	v_mfma_f32_16x16x32_bf16 v[84:87], v[154:157], v[210:213], v[84:87]
	v_mfma_f32_16x16x32_bf16 v[80:83], v[162:165], v[210:213], v[80:83]
	v_mfma_f32_16x16x32_bf16 v[124:127], v[158:161], v[190:193], v[124:127]
	v_mfma_f32_16x16x32_bf16 v[120:123], v[166:169], v[190:193], v[120:123]
	v_mfma_f32_16x16x32_bf16 v[116:119], v[158:161], v[198:201], v[116:119]
	v_mfma_f32_16x16x32_bf16 v[112:115], v[166:169], v[198:201], v[112:115]
	v_mfma_f32_16x16x32_bf16 v[100:103], v[158:161], v[206:209], v[100:103]
	v_mfma_f32_16x16x32_bf16 v[96:99], v[166:169], v[206:209], v[96:99]
	v_mfma_f32_16x16x32_bf16 v[84:87], v[158:161], v[214:217], v[84:87]
	v_mfma_f32_16x16x32_bf16 v[80:83], v[166:169], v[214:217], v[80:83]
	s_setprio 0
	s_setprio 1
	v_mfma_f32_16x16x32_bf16 v[108:111], v[170:173], v[186:189], v[108:111]
	v_mfma_f32_16x16x32_bf16 v[104:107], v[178:181], v[186:189], v[104:107]
	v_mfma_f32_16x16x32_bf16 v[92:95], v[170:173], v[194:197], v[92:95]
	v_mfma_f32_16x16x32_bf16 v[88:91], v[178:181], v[194:197], v[88:91]
	v_mfma_f32_16x16x32_bf16 v[76:79], v[170:173], v[202:205], v[76:79]
	v_mfma_f32_16x16x32_bf16 v[72:75], v[178:181], v[202:205], v[72:75]
	v_mfma_f32_16x16x32_bf16 v[68:71], v[170:173], v[210:213], v[68:71]
	v_mfma_f32_16x16x32_bf16 v[64:67], v[178:181], v[210:213], v[64:67]
	v_mfma_f32_16x16x32_bf16 v[108:111], v[174:177], v[190:193], v[108:111]
	v_mfma_f32_16x16x32_bf16 v[104:107], v[182:185], v[190:193], v[104:107]
	v_mfma_f32_16x16x32_bf16 v[92:95], v[174:177], v[198:201], v[92:95]
	v_mfma_f32_16x16x32_bf16 v[88:91], v[182:185], v[198:201], v[88:91]
	v_mfma_f32_16x16x32_bf16 v[76:79], v[174:177], v[206:209], v[76:79]
	v_mfma_f32_16x16x32_bf16 v[72:75], v[182:185], v[206:209], v[72:75]
	v_mfma_f32_16x16x32_bf16 v[68:71], v[174:177], v[214:217], v[68:71]
	v_mfma_f32_16x16x32_bf16 v[64:67], v[182:185], v[214:217], v[64:67]
	s_setprio 0
	s_barrier
	s_add_i32 s94, s86, s55
	v_lshl_add_u64 v[218:219], s[70:71], 0, v[130:131]
	s_mov_b32 m0, s94
	ds_read_b128 v[186:189], v153 offset:16384
	ds_read_b128 v[190:193], v153 offset:17408
	ds_read_b128 v[194:197], v153 offset:18432
	ds_read_b128 v[198:201], v153 offset:19456
	ds_read_b128 v[202:205], v153 offset:20480
	ds_read_b128 v[206:209], v153 offset:21504
	ds_read_b128 v[210:213], v153 offset:22528
	ds_read_b128 v[214:217], v153 offset:23552
	global_load_lds_dwordx4 v[218:219], off
	s_add_i32 m0, s94, 0x2000
	s_add_u32 s94, s70, 0x80000
	v_lshl_add_u64 v[220:221], s[70:71], 0, v[134:135]
	s_addc_u32 s95, s71, 0
	s_add_i32 s96, s87, s55
	global_load_lds_dwordx4 v[220:221], off
	v_lshl_add_u64 v[222:223], s[94:95], 0, v[130:131]
	s_mov_b32 m0, s96
	v_lshl_add_u64 v[224:225], s[72:73], 0, v[132:133]
	global_load_lds_dwordx4 v[222:223], off
	v_lshl_add_u64 v[222:223], s[94:95], 0, v[134:135]
	s_add_i32 m0, s96, 0x2000
	s_nop 0
	global_load_lds_dwordx4 v[222:223], off
	s_waitcnt vmcnt(6)
	s_waitcnt lgkmcnt(0)
	s_barrier
; #define PG8_STAGE(bufoff, gbase, voff) do { _Pragma("unroll") for (int _i = 0; _i < 2; ++_i) \
;         __builtin_amdgcn_global_load_lds((const unsigned*)((const char*)(gbase) + (voff)[_i]), (PG8_LAS unsigned*)(lds + (bufoff) + ldsw + _i * 8192), 16, 0, 0); } while (0)
; #define PG8_LDA(dst, b, h) do { _Pragma("unroll") for (int m = 0; m < 4; ++m) _Pragma("unroll") for (int k = 0; k < 2; ++k) dst[m][k] = *(const PG8_LAS bf16x8*)(lds + PG8_SA(b, h) + aoff + m * 2048 + k * 1024); } while (0)
; #define PG8_LDB(dst, b, h) do { _Pragma("unroll") for (int n = 0; n < 2; ++n) _Pragma("unroll") for (int k = 0; k < 2; ++k) dst[n][k] = *(const PG8_LAS bf16x8*)(lds + PG8_SB(b, h) + boff + n * 2048 + k * 1024); } while (0)
; #define PG8_MMA(ai, bj, At, Bt) do { __builtin_amdgcn_s_setprio(1); _Pragma("unroll") for (int m = 0; m < 4; ++m) _Pragma("unroll") for (int n = 0; n < 2; ++n) _Pragma("unroll") for (int k = 0; k < 2; ++k) \
;         acc[ai][bj][m][n] = __builtin_amdgcn_mfma_f32_16x16x32_bf16(Bt[n][k], At[m][k], acc[ai][bj][m][n], 0, 0, 0); __builtin_amdgcn_s_setprio(0); } while (0)
; #define PG8_WAIT_V(n) asm volatile("s_waitcnt vmcnt(" #n ")" ::: "memory")
; #define PG8_WAIT_L(n) asm volatile("s_waitcnt lgkmcnt(" #n ")" ::: "memory")
; #define PG8_BAR __builtin_amdgcn_s_barrier()
; #define PG8_SCHED __builtin_amdgcn_sched_barrier(0)
; template <class Epi, class Sched, bool ALIGN_EPI = false, bool SP2 = false>
; __device__ __forceinline__ void gemm_phase(PG8_LAS unsigned char* lds, const Gemm g, const Sched& S, const Epi& E) {
;     ...
;             PG8_WAIT_V(8); PG8_WAIT_L(0); PG8_BAR; PG8_MMA(1, 0, At, B0); PG8_MMA(1, 1, At, B1); PG8_BAR; PG8_SCHED;
;             PG8_LDB(B0, 1, 0); PG8_LDB(B1, 1, 1); PG8_SCHED; PG8_LDA(At, 1, 0); PG8_STAGE(PG8_SA(0, 1), a2 + hstep, voffA);
;             PG8_WAIT_V(8); PG8_WAIT_L(0); PG8_BAR; PG8_MMA(0, 0, At, B0); PG8_MMA(0, 1, At, B1); PG8_BAR; PG8_SCHED;
	s_setprio 1
	s_waitcnt lgkmcnt(0)
	v_mfma_f32_16x16x32_bf16 v[60:63], v[154:157], v[186:189], v[60:63]
	v_mfma_f32_16x16x32_bf16 v[56:59], v[162:165], v[186:189], v[56:59]
	v_mfma_f32_16x16x32_bf16 v[52:55], v[154:157], v[194:197], v[52:55]
	v_mfma_f32_16x16x32_bf16 v[48:51], v[162:165], v[194:197], v[48:51]
	v_mfma_f32_16x16x32_bf16 v[36:39], v[154:157], v[202:205], v[36:39]
	v_mfma_f32_16x16x32_bf16 v[32:35], v[162:165], v[202:205], v[32:35]
	v_mfma_f32_16x16x32_bf16 v[20:23], v[154:157], v[210:213], v[20:23]
	v_mfma_f32_16x16x32_bf16 v[16:19], v[162:165], v[210:213], v[16:19]
	v_mfma_f32_16x16x32_bf16 v[60:63], v[158:161], v[190:193], v[60:63]
	v_mfma_f32_16x16x32_bf16 v[56:59], v[166:169], v[190:193], v[56:59]
	v_mfma_f32_16x16x32_bf16 v[52:55], v[158:161], v[198:201], v[52:55]
	v_mfma_f32_16x16x32_bf16 v[48:51], v[166:169], v[198:201], v[48:51]
	v_mfma_f32_16x16x32_bf16 v[36:39], v[158:161], v[206:209], v[36:39]
	v_mfma_f32_16x16x32_bf16 v[32:35], v[166:169], v[206:209], v[32:35]
	v_mfma_f32_16x16x32_bf16 v[20:23], v[158:161], v[214:217], v[20:23]
	v_mfma_f32_16x16x32_bf16 v[16:19], v[166:169], v[214:217], v[16:19]
	s_setprio 0
	s_setprio 1
	v_mfma_f32_16x16x32_bf16 v[44:47], v[170:173], v[186:189], v[44:47]
	v_mfma_f32_16x16x32_bf16 v[40:43], v[178:181], v[186:189], v[40:43]
	v_mfma_f32_16x16x32_bf16 v[28:31], v[170:173], v[194:197], v[28:31]
	v_mfma_f32_16x16x32_bf16 v[24:27], v[178:181], v[194:197], v[24:27]
	v_mfma_f32_16x16x32_bf16 v[12:15], v[170:173], v[202:205], v[12:15]
	v_mfma_f32_16x16x32_bf16 v[8:11], v[178:181], v[202:205], v[8:11]
	v_mfma_f32_16x16x32_bf16 v[4:7], v[170:173], v[210:213], v[4:7]
	v_mfma_f32_16x16x32_bf16 v[0:3], v[178:181], v[210:213], v[0:3]
	v_mfma_f32_16x16x32_bf16 v[44:47], v[174:177], v[190:193], v[44:47]
	v_mfma_f32_16x16x32_bf16 v[40:43], v[182:185], v[190:193], v[40:43]
	v_mfma_f32_16x16x32_bf16 v[28:31], v[174:177], v[198:201], v[28:31]
	v_mfma_f32_16x16x32_bf16 v[24:27], v[182:185], v[198:201], v[24:27]
	v_mfma_f32_16x16x32_bf16 v[12:15], v[174:177], v[206:209], v[12:15]
	v_mfma_f32_16x16x32_bf16 v[8:11], v[182:185], v[206:209], v[8:11]
	v_mfma_f32_16x16x32_bf16 v[4:7], v[174:177], v[214:217], v[4:7]
	v_mfma_f32_16x16x32_bf16 v[0:3], v[182:185], v[214:217], v[0:3]
	s_setprio 0
	s_barrier
	v_lshl_add_u64 v[222:223], s[72:73], 0, v[128:129]
	s_mov_b32 m0, s19
	s_nop 0
	global_load_lds_dwordx4 v[222:223], off
	s_mov_b32 m0, s75
	s_nop 0
	global_load_lds_dwordx4 v[224:225], off
	s_add_i32 s94, 0, 0x18000
	s_add_i32 s95, 0, 0x1c000
	v_add_u32_e32 v166, s94, v149
	v_add_u32_e32 v182, s95, v149
	ds_read_b128 v[154:157], v166
	ds_read_b128 v[158:161], v166 offset:1024
	ds_read_b128 v[162:165], v166 offset:2048
	ds_read_b128 v[166:169], v166 offset:3072
	ds_read_b128 v[170:173], v182
	ds_read_b128 v[174:177], v182 offset:1024
	ds_read_b128 v[178:181], v182 offset:2048
	ds_read_b128 v[182:185], v182 offset:3072
	s_add_u32 s72, s72, 0x80000
	s_addc_u32 s73, s73, 0
	s_mov_b32 m0, s76
	v_lshl_add_u64 v[226:227], s[72:73], 0, v[128:129]
	ds_read_b128 v[186:189], v153 offset:32768
	ds_read_b128 v[190:193], v153 offset:33792
	ds_read_b128 v[194:197], v153 offset:34816
	ds_read_b128 v[198:201], v153 offset:35840
	ds_read_b128 v[202:205], v153 offset:36864
	ds_read_b128 v[206:209], v153 offset:37888
	ds_read_b128 v[210:213], v153 offset:38912
	ds_read_b128 v[214:217], v153 offset:39936
	global_load_lds_dwordx4 v[226:227], off
	v_lshl_add_u64 v[226:227], s[72:73], 0, v[132:133]
	s_mov_b32 m0, s77
	s_nop 0
	global_load_lds_dwordx4 v[226:227], off
	s_waitcnt vmcnt(8)
	s_waitcnt lgkmcnt(0)
	s_barrier
	s_setprio 1
	s_waitcnt lgkmcnt(0)
	v_mfma_f32_16x16x32_bf16 v[124:127], v[154:157], v[186:189], v[124:127]
	v_mfma_f32_16x16x32_bf16 v[120:123], v[162:165], v[186:189], v[120:123]
	v_mfma_f32_16x16x32_bf16 v[116:119], v[154:157], v[194:197], v[116:119]
	v_mfma_f32_16x16x32_bf16 v[112:115], v[162:165], v[194:197], v[112:115]
	v_mfma_f32_16x16x32_bf16 v[100:103], v[154:157], v[202:205], v[100:103]
	v_mfma_f32_16x16x32_bf16 v[96:99], v[162:165], v[202:205], v[96:99]
	v_mfma_f32_16x16x32_bf16 v[84:87], v[154:157], v[210:213], v[84:87]
	v_mfma_f32_16x16x32_bf16 v[80:83], v[162:165], v[210:213], v[80:83]
	v_mfma_f32_16x16x32_bf16 v[124:127], v[158:161], v[190:193], v[124:127]
	v_mfma_f32_16x16x32_bf16 v[120:123], v[166:169], v[190:193], v[120:123]
	v_mfma_f32_16x16x32_bf16 v[116:119], v[158:161], v[198:201], v[116:119]
	v_mfma_f32_16x16x32_bf16 v[112:115], v[166:169], v[198:201], v[112:115]
	v_mfma_f32_16x16x32_bf16 v[100:103], v[158:161], v[206:209], v[100:103]
	v_mfma_f32_16x16x32_bf16 v[96:99], v[166:169], v[206:209], v[96:99]
	v_mfma_f32_16x16x32_bf16 v[84:87], v[158:161], v[214:217], v[84:87]
	v_mfma_f32_16x16x32_bf16 v[80:83], v[166:169], v[214:217], v[80:83]
	s_setprio 0
	s_setprio 1
	v_mfma_f32_16x16x32_bf16 v[108:111], v[170:173], v[186:189], v[108:111]
	v_mfma_f32_16x16x32_bf16 v[104:107], v[178:181], v[186:189], v[104:107]
	v_mfma_f32_16x16x32_bf16 v[92:95], v[170:173], v[194:197], v[92:95]
	v_mfma_f32_16x16x32_bf16 v[88:91], v[178:181], v[194:197], v[88:91]
	v_mfma_f32_16x16x32_bf16 v[76:79], v[170:173], v[202:205], v[76:79]
	v_mfma_f32_16x16x32_bf16 v[72:75], v[178:181], v[202:205], v[72:75]
	v_mfma_f32_16x16x32_bf16 v[68:71], v[170:173], v[210:213], v[68:71]
	v_mfma_f32_16x16x32_bf16 v[64:67], v[178:181], v[210:213], v[64:67]
	v_mfma_f32_16x16x32_bf16 v[108:111], v[174:177], v[190:193], v[108:111]
	v_mfma_f32_16x16x32_bf16 v[104:107], v[182:185], v[190:193], v[104:107]
	v_mfma_f32_16x16x32_bf16 v[92:95], v[174:177], v[198:201], v[92:95]
	v_mfma_f32_16x16x32_bf16 v[88:91], v[182:185], v[198:201], v[88:91]
	v_mfma_f32_16x16x32_bf16 v[76:79], v[174:177], v[206:209], v[76:79]
	v_mfma_f32_16x16x32_bf16 v[72:75], v[182:185], v[206:209], v[72:75]
	v_mfma_f32_16x16x32_bf16 v[68:71], v[174:177], v[214:217], v[68:71]
	v_mfma_f32_16x16x32_bf16 v[64:67], v[182:185], v[214:217], v[64:67]
	s_setprio 0
	s_barrier
; #define PG8_STAGE(bufoff, gbase, voff) do { _Pragma("unroll") for (int _i = 0; _i < 2; ++_i) \
;         __builtin_amdgcn_global_load_lds((const unsigned*)((const char*)(gbase) + (voff)[_i]), (PG8_LAS unsigned*)(lds + (bufoff) + ldsw + _i * 8192), 16, 0, 0); } while (0)
; #define PG8_LDA(dst, b, h) do { _Pragma("unroll") for (int m = 0; m < 4; ++m) _Pragma("unroll") for (int k = 0; k < 2; ++k) dst[m][k] = *(const PG8_LAS bf16x8*)(lds + PG8_SA(b, h) + aoff + m * 2048 + k * 1024); } while (0)
; #define PG8_MMA(ai, bj, At, Bt) do { __builtin_amdgcn_s_setprio(1); _Pragma("unroll") for (int m = 0; m < 4; ++m) _Pragma("unroll") for (int n = 0; n < 2; ++n) _Pragma("unroll") for (int k = 0; k < 2; ++k) \
;         acc[ai][bj][m][n] = __builtin_amdgcn_mfma_f32_16x16x32_bf16(Bt[n][k], At[m][k], acc[ai][bj][m][n], 0, 0, 0); __builtin_amdgcn_s_setprio(0); } while (0)
; #define PG8_WAIT_V(n) asm volatile("s_waitcnt vmcnt(" #n ")" ::: "memory")
; #define PG8_WAIT_L(n) asm volatile("s_waitcnt lgkmcnt(" #n ")" ::: "memory")
; #define PG8_BAR __builtin_amdgcn_s_barrier()
; #define PG8_SCHED __builtin_amdgcn_sched_barrier(0)
; template <class Epi, class Sched, bool ALIGN_EPI = false, bool SP2 = false>
; __device__ __forceinline__ void gemm_phase(PG8_LAS unsigned char* lds, const Gemm g, const Sched& S, const Epi& E) {
;     ...
;             PG8_LDA(At, 1, 1); PG8_STAGE(PG8_SB(1, 0), b3, voffB); PG8_STAGE(PG8_SB(1, 1), b3 + hstep, voffB); PG8_STAGE(PG8_SA(1, 0), a3, voffA);
;             PG8_WAIT_V(8); PG8_WAIT_L(0); PG8_BAR; PG8_MMA(1, 0, At, B0); PG8_MMA(1, 1, At, B1); PG8_BAR; PG8_SCHED;
	s_add_i32 s72, s94, s55
	v_lshl_add_u64 v[218:219], v[218:219], 0, s[10:11]
	s_mov_b32 m0, s72
	ds_read_b128 v[186:189], v153 offset:49152
	ds_read_b128 v[190:193], v153 offset:50176
	ds_read_b128 v[194:197], v153 offset:51200
	ds_read_b128 v[198:201], v153 offset:52224
	ds_read_b128 v[202:205], v153 offset:53248
	ds_read_b128 v[206:209], v153 offset:54272
	ds_read_b128 v[210:213], v153 offset:55296
	ds_read_b128 v[214:217], v153 offset:56320
	global_load_lds_dwordx4 v[218:219], off
	s_add_i32 m0, s72, 0x2000
	s_add_u32 s70, s70, 0x80080
	v_lshl_add_u64 v[218:219], v[220:221], 0, s[10:11]
	s_addc_u32 s71, s71, 0
	s_add_i32 s72, s95, s55
	global_load_lds_dwordx4 v[218:219], off
	v_lshl_add_u64 v[218:219], s[70:71], 0, v[130:131]
	s_mov_b32 m0, s72
	s_nop 0
	global_load_lds_dwordx4 v[218:219], off
	v_lshl_add_u64 v[218:219], s[70:71], 0, v[134:135]
	s_add_i32 m0, s72, 0x2000
	s_nop 0
	global_load_lds_dwordx4 v[218:219], off
	v_lshl_add_u64 v[218:219], v[222:223], 0, s[10:11]
	s_mov_b32 m0, s79
	s_nop 0
	global_load_lds_dwordx4 v[218:219], off
	v_lshl_add_u64 v[218:219], v[224:225], 0, s[10:11]
	s_mov_b32 m0, s80
	s_nop 0
	global_load_lds_dwordx4 v[218:219], off
	s_waitcnt vmcnt(8)
	s_waitcnt lgkmcnt(0)
	s_barrier
	s_setprio 1
	s_waitcnt lgkmcnt(0)
	v_mfma_f32_16x16x32_bf16 v[60:63], v[154:157], v[186:189], v[60:63]
	v_mfma_f32_16x16x32_bf16 v[56:59], v[162:165], v[186:189], v[56:59]
	v_mfma_f32_16x16x32_bf16 v[52:55], v[154:157], v[194:197], v[52:55]
	v_mfma_f32_16x16x32_bf16 v[48:51], v[162:165], v[194:197], v[48:51]
	v_mfma_f32_16x16x32_bf16 v[36:39], v[154:157], v[202:205], v[36:39]
	v_mfma_f32_16x16x32_bf16 v[32:35], v[162:165], v[202:205], v[32:35]
	v_mfma_f32_16x16x32_bf16 v[20:23], v[154:157], v[210:213], v[20:23]
	v_mfma_f32_16x16x32_bf16 v[16:19], v[162:165], v[210:213], v[16:19]
	v_mfma_f32_16x16x32_bf16 v[60:63], v[158:161], v[190:193], v[60:63]
	v_mfma_f32_16x16x32_bf16 v[56:59], v[166:169], v[190:193], v[56:59]
	v_mfma_f32_16x16x32_bf16 v[52:55], v[158:161], v[198:201], v[52:55]
	v_mfma_f32_16x16x32_bf16 v[48:51], v[166:169], v[198:201], v[48:51]
	v_mfma_f32_16x16x32_bf16 v[36:39], v[158:161], v[206:209], v[36:39]
	v_mfma_f32_16x16x32_bf16 v[32:35], v[166:169], v[206:209], v[32:35]
	v_mfma_f32_16x16x32_bf16 v[20:23], v[158:161], v[214:217], v[20:23]
	v_mfma_f32_16x16x32_bf16 v[16:19], v[166:169], v[214:217], v[16:19]
	s_setprio 0
	s_setprio 1
	v_mfma_f32_16x16x32_bf16 v[44:47], v[170:173], v[186:189], v[44:47]
	v_mfma_f32_16x16x32_bf16 v[40:43], v[178:181], v[186:189], v[40:43]
	v_mfma_f32_16x16x32_bf16 v[28:31], v[170:173], v[194:197], v[28:31]
	v_mfma_f32_16x16x32_bf16 v[24:27], v[178:181], v[194:197], v[24:27]
	v_mfma_f32_16x16x32_bf16 v[12:15], v[170:173], v[202:205], v[12:15]
	v_mfma_f32_16x16x32_bf16 v[8:11], v[178:181], v[202:205], v[8:11]
	v_mfma_f32_16x16x32_bf16 v[4:7], v[170:173], v[210:213], v[4:7]
	v_mfma_f32_16x16x32_bf16 v[0:3], v[178:181], v[210:213], v[0:3]
	v_mfma_f32_16x16x32_bf16 v[44:47], v[174:177], v[190:193], v[44:47]
	v_mfma_f32_16x16x32_bf16 v[40:43], v[182:185], v[190:193], v[40:43]
	v_mfma_f32_16x16x32_bf16 v[28:31], v[174:177], v[198:201], v[28:31]
	v_mfma_f32_16x16x32_bf16 v[24:27], v[182:185], v[198:201], v[24:27]
	v_mfma_f32_16x16x32_bf16 v[12:15], v[174:177], v[206:209], v[12:15]
	v_mfma_f32_16x16x32_bf16 v[8:11], v[182:185], v[206:209], v[8:11]
	v_mfma_f32_16x16x32_bf16 v[4:7], v[174:177], v[214:217], v[4:7]
	v_mfma_f32_16x16x32_bf16 v[0:3], v[182:185], v[214:217], v[0:3]
	s_setprio 0
	s_barrier
	s_add_i32 s93, s93, 2
	s_add_u32 s68, s68, 0x100
	s_addc_u32 s69, s69, 0
	s_add_u32 s91, s91, 0x100
	s_addc_u32 s92, s92, 0
	s_cmp_gt_u32 s93, 29
	s_cbranch_scc0 .LBB0_119
	s_and_b64 vcc, exec, s[16:17]
	s_cbranch_vccz .LBB0_122
	s_barrier

; #define PG8_STAGE(bufoff, gbase, voff) do { _Pragma("unroll") for (int _i = 0; _i < 2; ++_i) \
;         __builtin_amdgcn_global_load_lds((const unsigned*)((const char*)(gbase) + (voff)[_i]), (PG8_LAS unsigned*)(lds + (bufoff) + ldsw + _i * 8192), 16, 0, 0); } while (0)
; #define PG8_LDA(dst, b, h) do { _Pragma("unroll") for (int m = 0; m < 4; ++m) _Pragma("unroll") for (int k = 0; k < 2; ++k) dst[m][k] = *(const PG8_LAS bf16x8*)(lds + PG8_SA(b, h) + aoff + m * 2048 + k * 1024); } while (0)
; #define PG8_LDB(dst, b, h) do { _Pragma("unroll") for (int n = 0; n < 2; ++n) _Pragma("unroll") for (int k = 0; k < 2; ++k) dst[n][k] = *(const PG8_LAS bf16x8*)(lds + PG8_SB(b, h) + boff + n * 2048 + k * 1024); } while (0)
; #define PG8_MMA(ai, bj, At, Bt) do { __builtin_amdgcn_s_setprio(1); _Pragma("unroll") for (int m = 0; m < 4; ++m) _Pragma("unroll") for (int n = 0; n < 2; ++n) _Pragma("unroll") for (int k = 0; k < 2; ++k) \
;         acc[ai][bj][m][n] = __builtin_amdgcn_mfma_f32_16x16x32_bf16(Bt[n][k], At[m][k], acc[ai][bj][m][n], 0, 0, 0); __builtin_amdgcn_s_setprio(0); } while (0)
; #define PG8_WAIT_V(n) asm volatile("s_waitcnt vmcnt(" #n ")" ::: "memory")
; #define PG8_WAIT_L(n) asm volatile("s_waitcnt lgkmcnt(" #n ")" ::: "memory")
; template <class Epi, class Sched, bool ALIGN_EPI = false, bool SP2 = false>
; __device__ __forceinline__ void gemm_phase(PG8_LAS unsigned char* lds, const Gemm g, const Sched& S, const Epi& E) {
;     ...
;             const bool last = (t == nt - 2);
;             const char* a1 = cA + (size_t)(t + 1) * kstep;
;             const char* a2 = last ? nA : cA + (size_t)(t + 2) * kstep; const char* b2 = last ? nB : cB + (size_t)(t + 2) * kstep;
;             const char* a3 = a2 + kstep; const char* b3 = b2 + kstep;
;             if (last && has_next) S.a_ready(nxt);
;             if constexpr (SP2) {
;             PG8_LDB(B0, 0, 0); PG8_LDB(B1, 0, 1); PG8_SCHED; PG8_LDA(At, 0, 0); PG8_STAGE(PG8_SA(1, 1), a1 + hstep, voffA);
;             PG8_WAIT_V(8); PG8_WAIT_L(0); PG8_BAR; PG8_MMA(0, 0, At, B0); PG8_MMA(0, 1, At, B1); PG8_BAR; PG8_SCHED;
;             PG8_LDA(At, 0, 1); PG8_STAGE(PG8_SB(0, 0), b2, voffB); PG8_STAGE(PG8_SB(0, 1), b2 + hstep, voffB); PG8_STAGE(PG8_SA(0, 0), a2, voffA);
;             PG8_WAIT_V(8); PG8_WAIT_L(0); PG8_BAR; PG8_MMA(1, 0, At, B0); PG8_MMA(1, 1, At, B1); PG8_BAR; PG8_SCHED;
.LBB0_559:
	ds_read_b128 v[148:151], v145
	ds_read_b128 v[152:155], v145 offset:1024
	ds_read_b128 v[156:159], v145 offset:2048
	ds_read_b128 v[160:163], v145 offset:3072
	ds_read_b128 v[164:167], v146
	ds_read_b128 v[168:171], v146 offset:1024
	ds_read_b128 v[172:175], v146 offset:2048
	ds_read_b128 v[176:179], v146 offset:3072
	s_add_u32 s38, s36, 0x100
	s_addc_u32 s39, s37, 0
	s_cmp_eq_u32 s85, 28
	s_cselect_b32 s67, s25, s39
	s_cselect_b32 s66, s81, s38
	s_cselect_b32 s45, s23, s84
	s_cselect_b32 s44, s82, s83
	v_lshl_add_u64 v[140:141], s[36:37], 0, v[132:133]
	s_add_i32 m0, s68, 0xc000
	ds_read_b128 v[180:183], v147
	ds_read_b128 v[184:187], v147 offset:1024
	ds_read_b128 v[188:191], v147 offset:2048
	ds_read_b128 v[192:195], v147 offset:3072
	ds_read_b128 v[196:199], v147 offset:4096
	ds_read_b128 v[200:203], v147 offset:5120
	ds_read_b128 v[204:207], v147 offset:6144
	ds_read_b128 v[208:211], v147 offset:7168
	global_load_lds_dwordx4 v[140:141], off
	v_lshl_add_u64 v[140:141], s[36:37], 0, v[134:135]
	s_add_i32 m0, s68, 0xe000
	s_nop 0
	global_load_lds_dwordx4 v[140:141], off
	s_waitcnt vmcnt(8)
	s_waitcnt lgkmcnt(0)
	s_barrier
	s_setprio 1
	s_waitcnt lgkmcnt(0)
	v_mfma_f32_16x16x32_bf16 v[124:127], v[148:151], v[180:183], v[124:127]
	v_mfma_f32_16x16x32_bf16 v[120:123], v[156:159], v[180:183], v[120:123]
	v_mfma_f32_16x16x32_bf16 v[112:115], v[148:151], v[188:191], v[112:115]
	v_mfma_f32_16x16x32_bf16 v[108:111], v[156:159], v[188:191], v[108:111]
	v_mfma_f32_16x16x32_bf16 v[96:99], v[148:151], v[196:199], v[96:99]
	v_mfma_f32_16x16x32_bf16 v[92:95], v[156:159], v[196:199], v[92:95]
	v_mfma_f32_16x16x32_bf16 v[80:83], v[148:151], v[204:207], v[80:83]
	v_mfma_f32_16x16x32_bf16 v[76:79], v[156:159], v[204:207], v[76:79]
	v_mfma_f32_16x16x32_bf16 v[124:127], v[152:155], v[184:187], v[124:127]
	v_mfma_f32_16x16x32_bf16 v[120:123], v[160:163], v[184:187], v[120:123]
	v_mfma_f32_16x16x32_bf16 v[112:115], v[152:155], v[192:195], v[112:115]
	v_mfma_f32_16x16x32_bf16 v[108:111], v[160:163], v[192:195], v[108:111]
	v_mfma_f32_16x16x32_bf16 v[96:99], v[152:155], v[200:203], v[96:99]
	v_mfma_f32_16x16x32_bf16 v[92:95], v[160:163], v[200:203], v[92:95]
	v_mfma_f32_16x16x32_bf16 v[80:83], v[152:155], v[208:211], v[80:83]
	v_mfma_f32_16x16x32_bf16 v[76:79], v[160:163], v[208:211], v[76:79]
	s_setprio 0
	s_setprio 1
	v_mfma_f32_16x16x32_bf16 v[116:119], v[164:167], v[180:183], v[116:119]
	v_mfma_f32_16x16x32_bf16 v[104:107], v[172:175], v[180:183], v[104:107]
	v_mfma_f32_16x16x32_bf16 v[100:103], v[164:167], v[188:191], v[100:103]
	v_mfma_f32_16x16x32_bf16 v[88:91], v[172:175], v[188:191], v[88:91]
	v_mfma_f32_16x16x32_bf16 v[84:87], v[164:167], v[196:199], v[84:87]
	v_mfma_f32_16x16x32_bf16 v[72:75], v[172:175], v[196:199], v[72:75]
	v_mfma_f32_16x16x32_bf16 v[68:71], v[164:167], v[204:207], v[68:71]
	v_mfma_f32_16x16x32_bf16 v[64:67], v[172:175], v[204:207], v[64:67]
	v_mfma_f32_16x16x32_bf16 v[116:119], v[168:171], v[184:187], v[116:119]
	v_mfma_f32_16x16x32_bf16 v[104:107], v[176:179], v[184:187], v[104:107]
	v_mfma_f32_16x16x32_bf16 v[100:103], v[168:171], v[192:195], v[100:103]
	v_mfma_f32_16x16x32_bf16 v[88:91], v[176:179], v[192:195], v[88:91]
	v_mfma_f32_16x16x32_bf16 v[84:87], v[168:171], v[200:203], v[84:87]
	v_mfma_f32_16x16x32_bf16 v[72:75], v[176:179], v[200:203], v[72:75]
	v_mfma_f32_16x16x32_bf16 v[68:71], v[168:171], v[208:211], v[68:71]
	v_mfma_f32_16x16x32_bf16 v[64:67], v[176:179], v[208:211], v[64:67]
	s_setprio 0
	s_barrier
	s_add_i32 s36, s79, s3
	v_lshl_add_u64 v[140:141], s[44:45], 0, v[130:131]
	s_mov_b32 m0, s36
	ds_read_b128 v[180:183], v147 offset:16384
	ds_read_b128 v[184:187], v147 offset:17408
	ds_read_b128 v[188:191], v147 offset:18432
	ds_read_b128 v[192:195], v147 offset:19456
	ds_read_b128 v[196:199], v147 offset:20480
	ds_read_b128 v[200:203], v147 offset:21504
	ds_read_b128 v[204:207], v147 offset:22528
	ds_read_b128 v[208:211], v147 offset:23552
	global_load_lds_dwordx4 v[140:141], off
	s_add_i32 m0, s36, 0x2000
	s_add_u32 s36, s44, 0x80000
	v_lshl_add_u64 v[212:213], s[44:45], 0, v[128:129]
	s_addc_u32 s37, s45, 0
	s_add_i32 s86, s80, s3
	global_load_lds_dwordx4 v[212:213], off
	v_lshl_add_u64 v[214:215], s[36:37], 0, v[130:131]
	s_mov_b32 m0, s86
	v_lshl_add_u64 v[216:217], s[66:67], 0, v[128:129]
	global_load_lds_dwordx4 v[214:215], off
	v_lshl_add_u64 v[214:215], s[36:37], 0, v[128:129]
	s_add_i32 m0, s86, 0x2000
	s_nop 0
	global_load_lds_dwordx4 v[214:215], off
	s_waitcnt vmcnt(6)
	s_waitcnt lgkmcnt(0)
	s_barrier
; #define PG8_STAGE(bufoff, gbase, voff) do { _Pragma("unroll") for (int _i = 0; _i < 2; ++_i) \
;         __builtin_amdgcn_global_load_lds((const unsigned*)((const char*)(gbase) + (voff)[_i]), (PG8_LAS unsigned*)(lds + (bufoff) + ldsw + _i * 8192), 16, 0, 0); } while (0)
; #define PG8_LDA(dst, b, h) do { _Pragma("unroll") for (int m = 0; m < 4; ++m) _Pragma("unroll") for (int k = 0; k < 2; ++k) dst[m][k] = *(const PG8_LAS bf16x8*)(lds + PG8_SA(b, h) + aoff + m * 2048 + k * 1024); } while (0)
; #define PG8_LDB(dst, b, h) do { _Pragma("unroll") for (int n = 0; n < 2; ++n) _Pragma("unroll") for (int k = 0; k < 2; ++k) dst[n][k] = *(const PG8_LAS bf16x8*)(lds + PG8_SB(b, h) + boff + n * 2048 + k * 1024); } while (0)
; #define PG8_MMA(ai, bj, At, Bt) do { __builtin_amdgcn_s_setprio(1); _Pragma("unroll") for (int m = 0; m < 4; ++m) _Pragma("unroll") for (int n = 0; n < 2; ++n) _Pragma("unroll") for (int k = 0; k < 2; ++k) \
;         acc[ai][bj][m][n] = __builtin_amdgcn_mfma_f32_16x16x32_bf16(Bt[n][k], At[m][k], acc[ai][bj][m][n], 0, 0, 0); __builtin_amdgcn_s_setprio(0); } while (0)
; #define PG8_WAIT_V(n) asm volatile("s_waitcnt vmcnt(" #n ")" ::: "memory")
; #define PG8_WAIT_L(n) asm volatile("s_waitcnt lgkmcnt(" #n ")" ::: "memory")
; #define PG8_BAR __builtin_amdgcn_s_barrier()
; #define PG8_SCHED __builtin_amdgcn_sched_barrier(0)
; template <class Epi, class Sched, bool ALIGN_EPI = false, bool SP2 = false>
; __device__ __forceinline__ void gemm_phase(PG8_LAS unsigned char* lds, const Gemm g, const Sched& S, const Epi& E) {
;     ...
;             PG8_WAIT_V(8); PG8_WAIT_L(0); PG8_BAR; PG8_MMA(1, 0, At, B0); PG8_MMA(1, 1, At, B1); PG8_BAR; PG8_SCHED;
;             PG8_LDB(B0, 1, 0); PG8_LDB(B1, 1, 1); PG8_SCHED; PG8_LDA(At, 1, 0); PG8_STAGE(PG8_SA(0, 1), a2 + hstep, voffA);
;             PG8_WAIT_V(8); PG8_WAIT_L(0); PG8_BAR; PG8_MMA(0, 0, At, B0); PG8_MMA(0, 1, At, B1); PG8_BAR; PG8_SCHED;
	s_setprio 1
	s_waitcnt lgkmcnt(0)
	v_mfma_f32_16x16x32_bf16 v[60:63], v[148:151], v[180:183], v[60:63]
	v_mfma_f32_16x16x32_bf16 v[56:59], v[156:159], v[180:183], v[56:59]
	v_mfma_f32_16x16x32_bf16 v[48:51], v[148:151], v[188:191], v[48:51]
	v_mfma_f32_16x16x32_bf16 v[44:47], v[156:159], v[188:191], v[44:47]
	v_mfma_f32_16x16x32_bf16 v[32:35], v[148:151], v[196:199], v[32:35]
	v_mfma_f32_16x16x32_bf16 v[28:31], v[156:159], v[196:199], v[28:31]
	v_mfma_f32_16x16x32_bf16 v[16:19], v[148:151], v[204:207], v[16:19]
	v_mfma_f32_16x16x32_bf16 v[12:15], v[156:159], v[204:207], v[12:15]
	v_mfma_f32_16x16x32_bf16 v[60:63], v[152:155], v[184:187], v[60:63]
	v_mfma_f32_16x16x32_bf16 v[56:59], v[160:163], v[184:187], v[56:59]
	v_mfma_f32_16x16x32_bf16 v[48:51], v[152:155], v[192:195], v[48:51]
	v_mfma_f32_16x16x32_bf16 v[44:47], v[160:163], v[192:195], v[44:47]
	v_mfma_f32_16x16x32_bf16 v[32:35], v[152:155], v[200:203], v[32:35]
	v_mfma_f32_16x16x32_bf16 v[28:31], v[160:163], v[200:203], v[28:31]
	v_mfma_f32_16x16x32_bf16 v[16:19], v[152:155], v[208:211], v[16:19]
	v_mfma_f32_16x16x32_bf16 v[12:15], v[160:163], v[208:211], v[12:15]
	s_setprio 0
	s_setprio 1
	v_mfma_f32_16x16x32_bf16 v[52:55], v[164:167], v[180:183], v[52:55]
	v_mfma_f32_16x16x32_bf16 v[40:43], v[172:175], v[180:183], v[40:43]
	v_mfma_f32_16x16x32_bf16 v[36:39], v[164:167], v[188:191], v[36:39]
	v_mfma_f32_16x16x32_bf16 v[24:27], v[172:175], v[188:191], v[24:27]
	v_mfma_f32_16x16x32_bf16 v[20:23], v[164:167], v[196:199], v[20:23]
	v_mfma_f32_16x16x32_bf16 v[8:11], v[172:175], v[196:199], v[8:11]
	v_mfma_f32_16x16x32_bf16 v[4:7], v[164:167], v[204:207], v[4:7]
	v_mfma_f32_16x16x32_bf16 v[0:3], v[172:175], v[204:207], v[0:3]
	v_mfma_f32_16x16x32_bf16 v[52:55], v[168:171], v[184:187], v[52:55]
	v_mfma_f32_16x16x32_bf16 v[40:43], v[176:179], v[184:187], v[40:43]
	v_mfma_f32_16x16x32_bf16 v[36:39], v[168:171], v[192:195], v[36:39]
	v_mfma_f32_16x16x32_bf16 v[24:27], v[176:179], v[192:195], v[24:27]
	v_mfma_f32_16x16x32_bf16 v[20:23], v[168:171], v[200:203], v[20:23]
	v_mfma_f32_16x16x32_bf16 v[8:11], v[176:179], v[200:203], v[8:11]
	v_mfma_f32_16x16x32_bf16 v[4:7], v[168:171], v[208:211], v[4:7]
	v_mfma_f32_16x16x32_bf16 v[0:3], v[176:179], v[208:211], v[0:3]
	s_setprio 0
	s_barrier
	v_lshl_add_u64 v[214:215], s[66:67], 0, v[130:131]
	s_mov_b32 m0, s68
	s_nop 0
	global_load_lds_dwordx4 v[214:215], off
	s_mov_b32 m0, s69
	s_nop 0
	global_load_lds_dwordx4 v[216:217], off
	s_add_i32 s86, 0, 0x18000
	s_add_i32 s87, 0, 0x1c000
	v_add_u32_e32 v160, s86, v143
	v_add_u32_e32 v176, s87, v143
	ds_read_b128 v[148:151], v160
	ds_read_b128 v[152:155], v160 offset:1024
	ds_read_b128 v[156:159], v160 offset:2048
	ds_read_b128 v[160:163], v160 offset:3072
	ds_read_b128 v[164:167], v176
	ds_read_b128 v[168:171], v176 offset:1024
	ds_read_b128 v[172:175], v176 offset:2048
	ds_read_b128 v[176:179], v176 offset:3072
	s_add_u32 s36, s66, 0x80000
	s_addc_u32 s37, s67, 0
	s_mov_b32 m0, s70
	v_lshl_add_u64 v[218:219], s[36:37], 0, v[130:131]
	ds_read_b128 v[180:183], v147 offset:32768
	ds_read_b128 v[184:187], v147 offset:33792
	ds_read_b128 v[188:191], v147 offset:34816
	ds_read_b128 v[192:195], v147 offset:35840
	ds_read_b128 v[196:199], v147 offset:36864
	ds_read_b128 v[200:203], v147 offset:37888
	ds_read_b128 v[204:207], v147 offset:38912
	ds_read_b128 v[208:211], v147 offset:39936
	global_load_lds_dwordx4 v[218:219], off
	v_lshl_add_u64 v[218:219], s[36:37], 0, v[128:129]
	s_mov_b32 m0, s71
	s_nop 0
	global_load_lds_dwordx4 v[218:219], off
	s_waitcnt vmcnt(8)
	s_waitcnt lgkmcnt(0)
	s_barrier
	s_setprio 1
	s_waitcnt lgkmcnt(0)
	v_mfma_f32_16x16x32_bf16 v[124:127], v[148:151], v[180:183], v[124:127]
	v_mfma_f32_16x16x32_bf16 v[120:123], v[156:159], v[180:183], v[120:123]
	v_mfma_f32_16x16x32_bf16 v[112:115], v[148:151], v[188:191], v[112:115]
	v_mfma_f32_16x16x32_bf16 v[108:111], v[156:159], v[188:191], v[108:111]
	v_mfma_f32_16x16x32_bf16 v[96:99], v[148:151], v[196:199], v[96:99]
	v_mfma_f32_16x16x32_bf16 v[92:95], v[156:159], v[196:199], v[92:95]
	v_mfma_f32_16x16x32_bf16 v[80:83], v[148:151], v[204:207], v[80:83]
	v_mfma_f32_16x16x32_bf16 v[76:79], v[156:159], v[204:207], v[76:79]
	v_mfma_f32_16x16x32_bf16 v[124:127], v[152:155], v[184:187], v[124:127]
	v_mfma_f32_16x16x32_bf16 v[120:123], v[160:163], v[184:187], v[120:123]
	v_mfma_f32_16x16x32_bf16 v[112:115], v[152:155], v[192:195], v[112:115]
	v_mfma_f32_16x16x32_bf16 v[108:111], v[160:163], v[192:195], v[108:111]
	v_mfma_f32_16x16x32_bf16 v[96:99], v[152:155], v[200:203], v[96:99]
	v_mfma_f32_16x16x32_bf16 v[92:95], v[160:163], v[200:203], v[92:95]
	v_mfma_f32_16x16x32_bf16 v[80:83], v[152:155], v[208:211], v[80:83]
	v_mfma_f32_16x16x32_bf16 v[76:79], v[160:163], v[208:211], v[76:79]
	s_setprio 0
	s_setprio 1
	v_mfma_f32_16x16x32_bf16 v[116:119], v[164:167], v[180:183], v[116:119]
	v_mfma_f32_16x16x32_bf16 v[104:107], v[172:175], v[180:183], v[104:107]
	v_mfma_f32_16x16x32_bf16 v[100:103], v[164:167], v[188:191], v[100:103]
	v_mfma_f32_16x16x32_bf16 v[88:91], v[172:175], v[188:191], v[88:91]
	v_mfma_f32_16x16x32_bf16 v[84:87], v[164:167], v[196:199], v[84:87]
	v_mfma_f32_16x16x32_bf16 v[72:75], v[172:175], v[196:199], v[72:75]
	v_mfma_f32_16x16x32_bf16 v[68:71], v[164:167], v[204:207], v[68:71]
	v_mfma_f32_16x16x32_bf16 v[64:67], v[172:175], v[204:207], v[64:67]
	v_mfma_f32_16x16x32_bf16 v[116:119], v[168:171], v[184:187], v[116:119]
	v_mfma_f32_16x16x32_bf16 v[104:107], v[176:179], v[184:187], v[104:107]
	v_mfma_f32_16x16x32_bf16 v[100:103], v[168:171], v[192:195], v[100:103]
	v_mfma_f32_16x16x32_bf16 v[88:91], v[176:179], v[192:195], v[88:91]
	v_mfma_f32_16x16x32_bf16 v[84:87], v[168:171], v[200:203], v[84:87]
	v_mfma_f32_16x16x32_bf16 v[72:75], v[176:179], v[200:203], v[72:75]
	v_mfma_f32_16x16x32_bf16 v[68:71], v[168:171], v[208:211], v[68:71]
	v_mfma_f32_16x16x32_bf16 v[64:67], v[176:179], v[208:211], v[64:67]
	s_setprio 0
	s_barrier
; #define PG8_STAGE(bufoff, gbase, voff) do { _Pragma("unroll") for (int _i = 0; _i < 2; ++_i) \
;         __builtin_amdgcn_global_load_lds((const unsigned*)((const char*)(gbase) + (voff)[_i]), (PG8_LAS unsigned*)(lds + (bufoff) + ldsw + _i * 8192), 16, 0, 0); } while (0)
; #define PG8_LDA(dst, b, h) do { _Pragma("unroll") for (int m = 0; m < 4; ++m) _Pragma("unroll") for (int k = 0; k < 2; ++k) dst[m][k] = *(const PG8_LAS bf16x8*)(lds + PG8_SA(b, h) + aoff + m * 2048 + k * 1024); } while (0)
; #define PG8_MMA(ai, bj, At, Bt) do { __builtin_amdgcn_s_setprio(1); _Pragma("unroll") for (int m = 0; m < 4; ++m) _Pragma("unroll") for (int n = 0; n < 2; ++n) _Pragma("unroll") for (int k = 0; k < 2; ++k) \
;         acc[ai][bj][m][n] = __builtin_amdgcn_mfma_f32_16x16x32_bf16(Bt[n][k], At[m][k], acc[ai][bj][m][n], 0, 0, 0); __builtin_amdgcn_s_setprio(0); } while (0)
; #define PG8_WAIT_V(n) asm volatile("s_waitcnt vmcnt(" #n ")" ::: "memory")
; #define PG8_WAIT_L(n) asm volatile("s_waitcnt lgkmcnt(" #n ")" ::: "memory")
; #define PG8_BAR __builtin_amdgcn_s_barrier()
; #define PG8_SCHED __builtin_amdgcn_sched_barrier(0)
; template <class Epi, class Sched, bool ALIGN_EPI = false, bool SP2 = false>
; __device__ __forceinline__ void gemm_phase(PG8_LAS unsigned char* lds, const Gemm g, const Sched& S, const Epi& E) {
;     ...
;             PG8_LDA(At, 1, 1); PG8_STAGE(PG8_SB(1, 0), b3, voffB); PG8_STAGE(PG8_SB(1, 1), b3 + hstep, voffB); PG8_STAGE(PG8_SA(1, 0), a3, voffA);
;             PG8_WAIT_V(8); PG8_WAIT_L(0); PG8_BAR; PG8_MMA(1, 0, At, B0); PG8_MMA(1, 1, At, B1); PG8_BAR; PG8_SCHED;
	s_add_i32 s36, s86, s3
	v_lshl_add_u64 v[140:141], v[140:141], 0, s[8:9]
	s_mov_b32 m0, s36
	ds_read_b128 v[180:183], v147 offset:49152
	ds_read_b128 v[184:187], v147 offset:50176
	ds_read_b128 v[188:191], v147 offset:51200
	ds_read_b128 v[192:195], v147 offset:52224
	ds_read_b128 v[196:199], v147 offset:53248
	ds_read_b128 v[200:203], v147 offset:54272
	ds_read_b128 v[204:207], v147 offset:55296
	ds_read_b128 v[208:211], v147 offset:56320
	global_load_lds_dwordx4 v[140:141], off
	s_add_i32 m0, s36, 0x2000
	s_add_u32 s36, s44, 0x80080
	v_lshl_add_u64 v[140:141], v[212:213], 0, s[8:9]
	s_addc_u32 s37, s45, 0
	s_add_i32 s44, s87, s3
	global_load_lds_dwordx4 v[140:141], off
	v_lshl_add_u64 v[140:141], s[36:37], 0, v[130:131]
	s_mov_b32 m0, s44
	s_nop 0
	global_load_lds_dwordx4 v[140:141], off
	v_lshl_add_u64 v[140:141], s[36:37], 0, v[128:129]
	s_add_i32 m0, s44, 0x2000
	s_nop 0
	global_load_lds_dwordx4 v[140:141], off
	v_lshl_add_u64 v[140:141], v[214:215], 0, s[8:9]
	s_mov_b32 m0, s75
	s_nop 0
	global_load_lds_dwordx4 v[140:141], off
	v_lshl_add_u64 v[140:141], v[216:217], 0, s[8:9]
	s_mov_b32 m0, s76
	s_nop 0
	global_load_lds_dwordx4 v[140:141], off
	s_waitcnt vmcnt(8)
	s_waitcnt lgkmcnt(0)
	s_barrier
	s_setprio 1
	s_waitcnt lgkmcnt(0)
	v_mfma_f32_16x16x32_bf16 v[60:63], v[148:151], v[180:183], v[60:63]
	v_mfma_f32_16x16x32_bf16 v[56:59], v[156:159], v[180:183], v[56:59]
	v_mfma_f32_16x16x32_bf16 v[48:51], v[148:151], v[188:191], v[48:51]
	v_mfma_f32_16x16x32_bf16 v[44:47], v[156:159], v[188:191], v[44:47]
	v_mfma_f32_16x16x32_bf16 v[32:35], v[148:151], v[196:199], v[32:35]
	v_mfma_f32_16x16x32_bf16 v[28:31], v[156:159], v[196:199], v[28:31]
	v_mfma_f32_16x16x32_bf16 v[16:19], v[148:151], v[204:207], v[16:19]
	v_mfma_f32_16x16x32_bf16 v[12:15], v[156:159], v[204:207], v[12:15]
	v_mfma_f32_16x16x32_bf16 v[60:63], v[152:155], v[184:187], v[60:63]
	v_mfma_f32_16x16x32_bf16 v[56:59], v[160:163], v[184:187], v[56:59]
	v_mfma_f32_16x16x32_bf16 v[48:51], v[152:155], v[192:195], v[48:51]
	v_mfma_f32_16x16x32_bf16 v[44:47], v[160:163], v[192:195], v[44:47]
	v_mfma_f32_16x16x32_bf16 v[32:35], v[152:155], v[200:203], v[32:35]
	v_mfma_f32_16x16x32_bf16 v[28:31], v[160:163], v[200:203], v[28:31]
	v_mfma_f32_16x16x32_bf16 v[16:19], v[152:155], v[208:211], v[16:19]
	v_mfma_f32_16x16x32_bf16 v[12:15], v[160:163], v[208:211], v[12:15]
	s_setprio 0
	s_setprio 1
	v_mfma_f32_16x16x32_bf16 v[52:55], v[164:167], v[180:183], v[52:55]
	v_mfma_f32_16x16x32_bf16 v[40:43], v[172:175], v[180:183], v[40:43]
	v_mfma_f32_16x16x32_bf16 v[36:39], v[164:167], v[188:191], v[36:39]
	v_mfma_f32_16x16x32_bf16 v[24:27], v[172:175], v[188:191], v[24:27]
	v_mfma_f32_16x16x32_bf16 v[20:23], v[164:167], v[196:199], v[20:23]
	v_mfma_f32_16x16x32_bf16 v[8:11], v[172:175], v[196:199], v[8:11]
	v_mfma_f32_16x16x32_bf16 v[4:7], v[164:167], v[204:207], v[4:7]
	v_mfma_f32_16x16x32_bf16 v[0:3], v[172:175], v[204:207], v[0:3]
	v_mfma_f32_16x16x32_bf16 v[52:55], v[168:171], v[184:187], v[52:55]
	v_mfma_f32_16x16x32_bf16 v[40:43], v[176:179], v[184:187], v[40:43]
	v_mfma_f32_16x16x32_bf16 v[36:39], v[168:171], v[192:195], v[36:39]
	v_mfma_f32_16x16x32_bf16 v[24:27], v[176:179], v[192:195], v[24:27]
	v_mfma_f32_16x16x32_bf16 v[20:23], v[168:171], v[200:203], v[20:23]
	v_mfma_f32_16x16x32_bf16 v[8:11], v[176:179], v[200:203], v[8:11]
	v_mfma_f32_16x16x32_bf16 v[4:7], v[168:171], v[208:211], v[4:7]
	v_mfma_f32_16x16x32_bf16 v[0:3], v[176:179], v[208:211], v[0:3]
	s_setprio 0
	s_barrier
	s_add_i32 s85, s85, 2
	s_add_u32 s83, s83, 0x100
	s_addc_u32 s84, s84, 0
	s_cmp_gt_u32 s85, 29
	s_mov_b64 s[36:37], s[38:39]
	s_cbranch_scc0 .LBB0_559
	s_and_b64 vcc, exec, s[10:11]
	s_cbranch_vccz .LBB0_562
	s_barrier

; #define PG8_STAGE(bufoff, gbase, voff) do { _Pragma("unroll") for (int _i = 0; _i < 2; ++_i) \
;         __builtin_amdgcn_global_load_lds((const unsigned*)((const char*)(gbase) + (voff)[_i]), (PG8_LAS unsigned*)(lds + (bufoff) + ldsw + _i * 8192), 16, 0, 0); } while (0)
; #define PG8_LDA(dst, b, h) do { _Pragma("unroll") for (int m = 0; m < 4; ++m) _Pragma("unroll") for (int k = 0; k < 2; ++k) dst[m][k] = *(const PG8_LAS bf16x8*)(lds + PG8_SA(b, h) + aoff + m * 2048 + k * 1024); } while (0)
; #define PG8_LDB(dst, b, h) do { _Pragma("unroll") for (int n = 0; n < 2; ++n) _Pragma("unroll") for (int k = 0; k < 2; ++k) dst[n][k] = *(const PG8_LAS bf16x8*)(lds + PG8_SB(b, h) + boff + n * 2048 + k * 1024); } while (0)
; #define PG8_MMA(ai, bj, At, Bt) do { __builtin_amdgcn_s_setprio(1); _Pragma("unroll") for (int m = 0; m < 4; ++m) _Pragma("unroll") for (int n = 0; n < 2; ++n) _Pragma("unroll") for (int k = 0; k < 2; ++k) \
;         acc[ai][bj][m][n] = __builtin_amdgcn_mfma_f32_16x16x32_bf16(Bt[n][k], At[m][k], acc[ai][bj][m][n], 0, 0, 0); __builtin_amdgcn_s_setprio(0); } while (0)
; #define PG8_WAIT_V(n) asm volatile("s_waitcnt vmcnt(" #n ")" ::: "memory")
; #define PG8_WAIT_L(n) asm volatile("s_waitcnt lgkmcnt(" #n ")" ::: "memory")
; template <class Epi, class Sched, bool ALIGN_EPI = false, bool SP2 = false>
; __device__ __forceinline__ void gemm_phase(PG8_LAS unsigned char* lds, const Gemm g, const Sched& S, const Epi& E) {
;     ...
;             const bool last = (t == nt - 2);
;             const char* a1 = cA + (size_t)(t + 1) * kstep;
;             const char* a2 = last ? nA : cA + (size_t)(t + 2) * kstep; const char* b2 = last ? nB : cB + (size_t)(t + 2) * kstep;
;             const char* a3 = a2 + kstep; const char* b3 = b2 + kstep;
;             if (last && has_next) S.a_ready(nxt);
;             if constexpr (SP2) {
;             PG8_LDB(B0, 0, 0); PG8_LDB(B1, 0, 1); PG8_SCHED; PG8_LDA(At, 0, 0); PG8_STAGE(PG8_SA(1, 1), a1 + hstep, voffA);
;             PG8_WAIT_V(8); PG8_WAIT_L(0); PG8_BAR; PG8_MMA(0, 0, At, B0); PG8_MMA(0, 1, At, B1); PG8_BAR; PG8_SCHED;
;             PG8_LDA(At, 0, 1); PG8_STAGE(PG8_SB(0, 0), b2, voffB); PG8_STAGE(PG8_SB(0, 1), b2 + hstep, voffB); PG8_STAGE(PG8_SA(0, 0), a2, voffA);
;             PG8_WAIT_V(8); PG8_WAIT_L(0); PG8_BAR; PG8_MMA(1, 0, At, B0); PG8_MMA(1, 1, At, B1); PG8_BAR; PG8_SCHED;
.LBB0_704:
	s_add_u32 s10, s8, 0xfff80080
	s_addc_u32 s11, s9, -1
	s_add_i32 s35, 0, 0x10000
	s_cmp_eq_u32 s34, 28
	s_cselect_b32 s13, s31, s11
	s_cselect_b32 s12, s74, s10
	v_add_u32_e32 v142, s35, v146
	s_cselect_b32 s11, s39, vcc_hi
	s_cselect_b32 s10, s89, vcc_lo
	s_add_i32 s54, 0, 0x14000
	ds_read_b128 v[150:153], v142
	ds_read_b128 v[154:157], v142 offset:1024
	ds_read_b128 v[158:161], v142 offset:2048
	ds_read_b128 v[162:165], v142 offset:3072
	v_add_u32_e32 v142, s54, v146
	ds_read_b128 v[166:169], v142
	ds_read_b128 v[170:173], v142 offset:1024
	ds_read_b128 v[174:177], v142 offset:2048
	ds_read_b128 v[178:181], v142 offset:3072
	v_lshl_add_u64 v[142:143], s[8:9], 0, v[136:137]
	s_add_i32 m0, s25, 0xc000
	ds_read_b128 v[182:185], v148
	ds_read_b128 v[186:189], v148 offset:1024
	ds_read_b128 v[190:193], v148 offset:2048
	ds_read_b128 v[194:197], v148 offset:3072
	ds_read_b128 v[198:201], v148 offset:4096
	ds_read_b128 v[202:205], v148 offset:5120
	ds_read_b128 v[206:209], v148 offset:6144
	ds_read_b128 v[210:213], v148 offset:7168
	global_load_lds_dwordx4 v[142:143], off
	v_lshl_add_u64 v[142:143], s[8:9], 0, v[138:139]
	s_add_i32 m0, s25, 0xe000
	s_nop 0
	global_load_lds_dwordx4 v[142:143], off
	s_waitcnt vmcnt(8)
	s_waitcnt lgkmcnt(0)
	s_barrier
	s_setprio 1
	s_waitcnt lgkmcnt(0)
	v_mfma_f32_16x16x32_bf16 v[124:127], v[150:153], v[182:185], v[124:127]
	v_mfma_f32_16x16x32_bf16 v[120:123], v[158:161], v[182:185], v[120:123]
	v_mfma_f32_16x16x32_bf16 v[108:111], v[150:153], v[190:193], v[108:111]
	v_mfma_f32_16x16x32_bf16 v[104:107], v[158:161], v[190:193], v[104:107]
	v_mfma_f32_16x16x32_bf16 v[92:95], v[150:153], v[198:201], v[92:95]
	v_mfma_f32_16x16x32_bf16 v[88:91], v[158:161], v[198:201], v[88:91]
	v_mfma_f32_16x16x32_bf16 v[76:79], v[150:153], v[206:209], v[76:79]
	v_mfma_f32_16x16x32_bf16 v[72:75], v[158:161], v[206:209], v[72:75]
	v_mfma_f32_16x16x32_bf16 v[124:127], v[154:157], v[186:189], v[124:127]
	v_mfma_f32_16x16x32_bf16 v[120:123], v[162:165], v[186:189], v[120:123]
	v_mfma_f32_16x16x32_bf16 v[108:111], v[154:157], v[194:197], v[108:111]
	v_mfma_f32_16x16x32_bf16 v[104:107], v[162:165], v[194:197], v[104:107]
	v_mfma_f32_16x16x32_bf16 v[92:95], v[154:157], v[202:205], v[92:95]
	v_mfma_f32_16x16x32_bf16 v[88:91], v[162:165], v[202:205], v[88:91]
	v_mfma_f32_16x16x32_bf16 v[76:79], v[154:157], v[210:213], v[76:79]
	v_mfma_f32_16x16x32_bf16 v[72:75], v[162:165], v[210:213], v[72:75]
	s_setprio 0
	s_setprio 1
	v_mfma_f32_16x16x32_bf16 v[116:119], v[166:169], v[182:185], v[116:119]
	v_mfma_f32_16x16x32_bf16 v[112:115], v[174:177], v[182:185], v[112:115]
	v_mfma_f32_16x16x32_bf16 v[100:103], v[166:169], v[190:193], v[100:103]
	v_mfma_f32_16x16x32_bf16 v[96:99], v[174:177], v[190:193], v[96:99]
	v_mfma_f32_16x16x32_bf16 v[84:87], v[166:169], v[198:201], v[84:87]
	v_mfma_f32_16x16x32_bf16 v[80:83], v[174:177], v[198:201], v[80:83]
	v_mfma_f32_16x16x32_bf16 v[68:71], v[166:169], v[206:209], v[68:71]
	v_mfma_f32_16x16x32_bf16 v[64:67], v[174:177], v[206:209], v[64:67]
	v_mfma_f32_16x16x32_bf16 v[116:119], v[170:173], v[186:189], v[116:119]
	v_mfma_f32_16x16x32_bf16 v[112:115], v[178:181], v[186:189], v[112:115]
	v_mfma_f32_16x16x32_bf16 v[100:103], v[170:173], v[194:197], v[100:103]
	v_mfma_f32_16x16x32_bf16 v[96:99], v[178:181], v[194:197], v[96:99]
	v_mfma_f32_16x16x32_bf16 v[84:87], v[170:173], v[202:205], v[84:87]
	v_mfma_f32_16x16x32_bf16 v[80:83], v[178:181], v[202:205], v[80:83]
	v_mfma_f32_16x16x32_bf16 v[68:71], v[170:173], v[210:213], v[68:71]
	v_mfma_f32_16x16x32_bf16 v[64:67], v[178:181], v[210:213], v[64:67]
	s_setprio 0
	s_barrier
	s_add_i32 s35, s35, s24
	v_lshl_add_u64 v[142:143], s[10:11], 0, v[128:129]
	s_mov_b32 m0, s35
	ds_read_b128 v[182:185], v148 offset:16384
	ds_read_b128 v[186:189], v148 offset:17408
	ds_read_b128 v[190:193], v148 offset:18432
	ds_read_b128 v[194:197], v148 offset:19456
	ds_read_b128 v[198:201], v148 offset:20480
	ds_read_b128 v[202:205], v148 offset:21504
	ds_read_b128 v[206:209], v148 offset:22528
	ds_read_b128 v[210:213], v148 offset:23552
	global_load_lds_dwordx4 v[142:143], off
	s_add_i32 m0, s35, 0x2000
	s_add_u32 s80, s10, 0x80000
	v_lshl_add_u64 v[214:215], s[10:11], 0, v[134:135]
	s_addc_u32 s81, s11, 0
	s_add_i32 s35, s54, s24
	global_load_lds_dwordx4 v[214:215], off
	v_lshl_add_u64 v[216:217], s[80:81], 0, v[128:129]
	s_mov_b32 m0, s35
	v_lshl_add_u64 v[218:219], s[12:13], 0, v[132:133]
	global_load_lds_dwordx4 v[216:217], off
	v_lshl_add_u64 v[216:217], s[80:81], 0, v[134:135]
	s_add_i32 m0, s35, 0x2000
	s_nop 0
	global_load_lds_dwordx4 v[216:217], off
	s_waitcnt vmcnt(6)
	s_waitcnt lgkmcnt(0)
	s_barrier
; #define PG8_STAGE(bufoff, gbase, voff) do { _Pragma("unroll") for (int _i = 0; _i < 2; ++_i) \
;         __builtin_amdgcn_global_load_lds((const unsigned*)((const char*)(gbase) + (voff)[_i]), (PG8_LAS unsigned*)(lds + (bufoff) + ldsw + _i * 8192), 16, 0, 0); } while (0)
; #define PG8_LDA(dst, b, h) do { _Pragma("unroll") for (int m = 0; m < 4; ++m) _Pragma("unroll") for (int k = 0; k < 2; ++k) dst[m][k] = *(const PG8_LAS bf16x8*)(lds + PG8_SA(b, h) + aoff + m * 2048 + k * 1024); } while (0)
; #define PG8_LDB(dst, b, h) do { _Pragma("unroll") for (int n = 0; n < 2; ++n) _Pragma("unroll") for (int k = 0; k < 2; ++k) dst[n][k] = *(const PG8_LAS bf16x8*)(lds + PG8_SB(b, h) + boff + n * 2048 + k * 1024); } while (0)
; #define PG8_MMA(ai, bj, At, Bt) do { __builtin_amdgcn_s_setprio(1); _Pragma("unroll") for (int m = 0; m < 4; ++m) _Pragma("unroll") for (int n = 0; n < 2; ++n) _Pragma("unroll") for (int k = 0; k < 2; ++k) \
;         acc[ai][bj][m][n] = __builtin_amdgcn_mfma_f32_16x16x32_bf16(Bt[n][k], At[m][k], acc[ai][bj][m][n], 0, 0, 0); __builtin_amdgcn_s_setprio(0); } while (0)
; #define PG8_WAIT_V(n) asm volatile("s_waitcnt vmcnt(" #n ")" ::: "memory")
; #define PG8_WAIT_L(n) asm volatile("s_waitcnt lgkmcnt(" #n ")" ::: "memory")
; #define PG8_BAR __builtin_amdgcn_s_barrier()
; #define PG8_SCHED __builtin_amdgcn_sched_barrier(0)
; template <class Epi, class Sched, bool ALIGN_EPI = false, bool SP2 = false>
; __device__ __forceinline__ void gemm_phase(PG8_LAS unsigned char* lds, const Gemm g, const Sched& S, const Epi& E) {
;     ...
;             PG8_WAIT_V(8); PG8_WAIT_L(0); PG8_BAR; PG8_MMA(1, 0, At, B0); PG8_MMA(1, 1, At, B1); PG8_BAR; PG8_SCHED;
;             PG8_LDB(B0, 1, 0); PG8_LDB(B1, 1, 1); PG8_SCHED; PG8_LDA(At, 1, 0); PG8_STAGE(PG8_SA(0, 1), a2 + hstep, voffA);
;             PG8_WAIT_V(8); PG8_WAIT_L(0); PG8_BAR; PG8_MMA(0, 0, At, B0); PG8_MMA(0, 1, At, B1); PG8_BAR; PG8_SCHED;
	s_setprio 1
	s_waitcnt lgkmcnt(0)
	v_mfma_f32_16x16x32_bf16 v[60:63], v[150:153], v[182:185], v[60:63]
	v_mfma_f32_16x16x32_bf16 v[56:59], v[158:161], v[182:185], v[56:59]
	v_mfma_f32_16x16x32_bf16 v[44:47], v[150:153], v[190:193], v[44:47]
	v_mfma_f32_16x16x32_bf16 v[40:43], v[158:161], v[190:193], v[40:43]
	v_mfma_f32_16x16x32_bf16 v[28:31], v[150:153], v[198:201], v[28:31]
	v_mfma_f32_16x16x32_bf16 v[24:27], v[158:161], v[198:201], v[24:27]
	v_mfma_f32_16x16x32_bf16 v[12:15], v[150:153], v[206:209], v[12:15]
	v_mfma_f32_16x16x32_bf16 v[8:11], v[158:161], v[206:209], v[8:11]
	v_mfma_f32_16x16x32_bf16 v[60:63], v[154:157], v[186:189], v[60:63]
	v_mfma_f32_16x16x32_bf16 v[56:59], v[162:165], v[186:189], v[56:59]
	v_mfma_f32_16x16x32_bf16 v[44:47], v[154:157], v[194:197], v[44:47]
	v_mfma_f32_16x16x32_bf16 v[40:43], v[162:165], v[194:197], v[40:43]
	v_mfma_f32_16x16x32_bf16 v[28:31], v[154:157], v[202:205], v[28:31]
	v_mfma_f32_16x16x32_bf16 v[24:27], v[162:165], v[202:205], v[24:27]
	v_mfma_f32_16x16x32_bf16 v[12:15], v[154:157], v[210:213], v[12:15]
	v_mfma_f32_16x16x32_bf16 v[8:11], v[162:165], v[210:213], v[8:11]
	s_setprio 0
	s_setprio 1
	v_mfma_f32_16x16x32_bf16 v[52:55], v[166:169], v[182:185], v[52:55]
	v_mfma_f32_16x16x32_bf16 v[48:51], v[174:177], v[182:185], v[48:51]
	v_mfma_f32_16x16x32_bf16 v[36:39], v[166:169], v[190:193], v[36:39]
	v_mfma_f32_16x16x32_bf16 v[32:35], v[174:177], v[190:193], v[32:35]
	v_mfma_f32_16x16x32_bf16 v[20:23], v[166:169], v[198:201], v[20:23]
	v_mfma_f32_16x16x32_bf16 v[16:19], v[174:177], v[198:201], v[16:19]
	v_mfma_f32_16x16x32_bf16 v[4:7], v[166:169], v[206:209], v[4:7]
	v_mfma_f32_16x16x32_bf16 v[0:3], v[174:177], v[206:209], v[0:3]
	v_mfma_f32_16x16x32_bf16 v[52:55], v[170:173], v[186:189], v[52:55]
	v_mfma_f32_16x16x32_bf16 v[48:51], v[178:181], v[186:189], v[48:51]
	v_mfma_f32_16x16x32_bf16 v[36:39], v[170:173], v[194:197], v[36:39]
	v_mfma_f32_16x16x32_bf16 v[32:35], v[178:181], v[194:197], v[32:35]
	v_mfma_f32_16x16x32_bf16 v[20:23], v[170:173], v[202:205], v[20:23]
	v_mfma_f32_16x16x32_bf16 v[16:19], v[178:181], v[202:205], v[16:19]
	v_mfma_f32_16x16x32_bf16 v[4:7], v[170:173], v[210:213], v[4:7]
	v_mfma_f32_16x16x32_bf16 v[0:3], v[178:181], v[210:213], v[0:3]
	s_setprio 0
	s_barrier
	v_lshl_add_u64 v[216:217], s[12:13], 0, v[130:131]
	s_mov_b32 m0, s25
	s_nop 0
	global_load_lds_dwordx4 v[216:217], off
	s_mov_b32 m0, s26
	s_nop 0
	global_load_lds_dwordx4 v[218:219], off
	s_add_i32 s35, 0, 0x18000
	v_add_u32_e32 v149, s35, v146
	s_add_i32 s54, 0, 0x1c000
	ds_read_b128 v[150:153], v149
	ds_read_b128 v[154:157], v149 offset:1024
	ds_read_b128 v[158:161], v149 offset:2048
	ds_read_b128 v[162:165], v149 offset:3072
	v_add_u32_e32 v149, s54, v146
	ds_read_b128 v[166:169], v149
	ds_read_b128 v[170:173], v149 offset:1024
	ds_read_b128 v[174:177], v149 offset:2048
	ds_read_b128 v[178:181], v149 offset:3072
	s_add_u32 s12, s12, 0x80000
	s_addc_u32 s13, s13, 0
	s_mov_b32 m0, s27
	v_lshl_add_u64 v[220:221], s[12:13], 0, v[130:131]
	ds_read_b128 v[182:185], v148 offset:32768
	ds_read_b128 v[186:189], v148 offset:33792
	ds_read_b128 v[190:193], v148 offset:34816
	ds_read_b128 v[194:197], v148 offset:35840
	ds_read_b128 v[198:201], v148 offset:36864
	ds_read_b128 v[202:205], v148 offset:37888
	ds_read_b128 v[206:209], v148 offset:38912
	ds_read_b128 v[210:213], v148 offset:39936
	global_load_lds_dwordx4 v[220:221], off
	v_lshl_add_u64 v[220:221], s[12:13], 0, v[132:133]
	s_mov_b32 m0, s28
	s_nop 0
	global_load_lds_dwordx4 v[220:221], off
	s_waitcnt vmcnt(8)
	s_waitcnt lgkmcnt(0)
	s_barrier
	s_setprio 1
	s_waitcnt lgkmcnt(0)
	v_mfma_f32_16x16x32_bf16 v[124:127], v[150:153], v[182:185], v[124:127]
	v_mfma_f32_16x16x32_bf16 v[120:123], v[158:161], v[182:185], v[120:123]
	v_mfma_f32_16x16x32_bf16 v[108:111], v[150:153], v[190:193], v[108:111]
	v_mfma_f32_16x16x32_bf16 v[104:107], v[158:161], v[190:193], v[104:107]
	v_mfma_f32_16x16x32_bf16 v[92:95], v[150:153], v[198:201], v[92:95]
	v_mfma_f32_16x16x32_bf16 v[88:91], v[158:161], v[198:201], v[88:91]
	v_mfma_f32_16x16x32_bf16 v[76:79], v[150:153], v[206:209], v[76:79]
	v_mfma_f32_16x16x32_bf16 v[72:75], v[158:161], v[206:209], v[72:75]
	v_mfma_f32_16x16x32_bf16 v[124:127], v[154:157], v[186:189], v[124:127]
	v_mfma_f32_16x16x32_bf16 v[120:123], v[162:165], v[186:189], v[120:123]
	v_mfma_f32_16x16x32_bf16 v[108:111], v[154:157], v[194:197], v[108:111]
	v_mfma_f32_16x16x32_bf16 v[104:107], v[162:165], v[194:197], v[104:107]
	v_mfma_f32_16x16x32_bf16 v[92:95], v[154:157], v[202:205], v[92:95]
	v_mfma_f32_16x16x32_bf16 v[88:91], v[162:165], v[202:205], v[88:91]
	v_mfma_f32_16x16x32_bf16 v[76:79], v[154:157], v[210:213], v[76:79]
	v_mfma_f32_16x16x32_bf16 v[72:75], v[162:165], v[210:213], v[72:75]
	s_setprio 0
	s_setprio 1
	v_mfma_f32_16x16x32_bf16 v[116:119], v[166:169], v[182:185], v[116:119]
	v_mfma_f32_16x16x32_bf16 v[112:115], v[174:177], v[182:185], v[112:115]
	v_mfma_f32_16x16x32_bf16 v[100:103], v[166:169], v[190:193], v[100:103]
	v_mfma_f32_16x16x32_bf16 v[96:99], v[174:177], v[190:193], v[96:99]
	v_mfma_f32_16x16x32_bf16 v[84:87], v[166:169], v[198:201], v[84:87]
	v_mfma_f32_16x16x32_bf16 v[80:83], v[174:177], v[198:201], v[80:83]
	v_mfma_f32_16x16x32_bf16 v[68:71], v[166:169], v[206:209], v[68:71]
	v_mfma_f32_16x16x32_bf16 v[64:67], v[174:177], v[206:209], v[64:67]
	v_mfma_f32_16x16x32_bf16 v[116:119], v[170:173], v[186:189], v[116:119]
	v_mfma_f32_16x16x32_bf16 v[112:115], v[178:181], v[186:189], v[112:115]
	v_mfma_f32_16x16x32_bf16 v[100:103], v[170:173], v[194:197], v[100:103]
	v_mfma_f32_16x16x32_bf16 v[96:99], v[178:181], v[194:197], v[96:99]
	v_mfma_f32_16x16x32_bf16 v[84:87], v[170:173], v[202:205], v[84:87]
	v_mfma_f32_16x16x32_bf16 v[80:83], v[178:181], v[202:205], v[80:83]
	v_mfma_f32_16x16x32_bf16 v[68:71], v[170:173], v[210:213], v[68:71]
	v_mfma_f32_16x16x32_bf16 v[64:67], v[178:181], v[210:213], v[64:67]
	s_setprio 0
	s_barrier
; #define PG8_STAGE(bufoff, gbase, voff) do { _Pragma("unroll") for (int _i = 0; _i < 2; ++_i) \
;         __builtin_amdgcn_global_load_lds((const unsigned*)((const char*)(gbase) + (voff)[_i]), (PG8_LAS unsigned*)(lds + (bufoff) + ldsw + _i * 8192), 16, 0, 0); } while (0)
; #define PG8_LDA(dst, b, h) do { _Pragma("unroll") for (int m = 0; m < 4; ++m) _Pragma("unroll") for (int k = 0; k < 2; ++k) dst[m][k] = *(const PG8_LAS bf16x8*)(lds + PG8_SA(b, h) + aoff + m * 2048 + k * 1024); } while (0)
; #define PG8_MMA(ai, bj, At, Bt) do { __builtin_amdgcn_s_setprio(1); _Pragma("unroll") for (int m = 0; m < 4; ++m) _Pragma("unroll") for (int n = 0; n < 2; ++n) _Pragma("unroll") for (int k = 0; k < 2; ++k) \
;         acc[ai][bj][m][n] = __builtin_amdgcn_mfma_f32_16x16x32_bf16(Bt[n][k], At[m][k], acc[ai][bj][m][n], 0, 0, 0); __builtin_amdgcn_s_setprio(0); } while (0)
; #define PG8_WAIT_V(n) asm volatile("s_waitcnt vmcnt(" #n ")" ::: "memory")
; #define PG8_WAIT_L(n) asm volatile("s_waitcnt lgkmcnt(" #n ")" ::: "memory")
; #define PG8_BAR __builtin_amdgcn_s_barrier()
; #define PG8_SCHED __builtin_amdgcn_sched_barrier(0)
; template <class Epi, class Sched, bool ALIGN_EPI = false, bool SP2 = false>
; __device__ __forceinline__ void gemm_phase(PG8_LAS unsigned char* lds, const Gemm g, const Sched& S, const Epi& E) {
;     ...
;             PG8_LDA(At, 1, 1); PG8_STAGE(PG8_SB(1, 0), b3, voffB); PG8_STAGE(PG8_SB(1, 1), b3 + hstep, voffB); PG8_STAGE(PG8_SA(1, 0), a3, voffA);
;             PG8_WAIT_V(8); PG8_WAIT_L(0); PG8_BAR; PG8_MMA(1, 0, At, B0); PG8_MMA(1, 1, At, B1); PG8_BAR; PG8_SCHED;
	s_add_i32 s12, s35, s24
	v_lshl_add_u64 v[142:143], v[142:143], 0, s[84:85]
	s_mov_b32 m0, s12
	ds_read_b128 v[182:185], v148 offset:49152
	ds_read_b128 v[186:189], v148 offset:50176
	ds_read_b128 v[190:193], v148 offset:51200
	ds_read_b128 v[194:197], v148 offset:52224
	ds_read_b128 v[198:201], v148 offset:53248
	ds_read_b128 v[202:205], v148 offset:54272
	ds_read_b128 v[206:209], v148 offset:55296
	ds_read_b128 v[210:213], v148 offset:56320
	global_load_lds_dwordx4 v[142:143], off
	s_add_i32 m0, s12, 0x2000
	s_add_u32 s10, s10, 0x80080
	v_lshl_add_u64 v[142:143], v[214:215], 0, s[84:85]
	s_addc_u32 s11, s11, 0
	s_add_i32 s12, s54, s24
	global_load_lds_dwordx4 v[142:143], off
	v_lshl_add_u64 v[142:143], s[10:11], 0, v[128:129]
	s_mov_b32 m0, s12
	s_nop 0
	global_load_lds_dwordx4 v[142:143], off
	v_lshl_add_u64 v[142:143], s[10:11], 0, v[134:135]
	s_add_i32 m0, s12, 0x2000
	s_nop 0
	global_load_lds_dwordx4 v[142:143], off
	v_lshl_add_u64 v[142:143], v[216:217], 0, s[84:85]
	s_mov_b32 m0, s29
	s_nop 0
	global_load_lds_dwordx4 v[142:143], off
	v_lshl_add_u64 v[142:143], v[218:219], 0, s[84:85]
	s_mov_b32 m0, s90
	s_nop 0
	global_load_lds_dwordx4 v[142:143], off
	s_waitcnt vmcnt(8)
	s_waitcnt lgkmcnt(0)
	s_barrier
	s_setprio 1
	s_waitcnt lgkmcnt(0)
	v_mfma_f32_16x16x32_bf16 v[60:63], v[150:153], v[182:185], v[60:63]
	v_mfma_f32_16x16x32_bf16 v[56:59], v[158:161], v[182:185], v[56:59]
	v_mfma_f32_16x16x32_bf16 v[44:47], v[150:153], v[190:193], v[44:47]
	v_mfma_f32_16x16x32_bf16 v[40:43], v[158:161], v[190:193], v[40:43]
	v_mfma_f32_16x16x32_bf16 v[28:31], v[150:153], v[198:201], v[28:31]
	v_mfma_f32_16x16x32_bf16 v[24:27], v[158:161], v[198:201], v[24:27]
	v_mfma_f32_16x16x32_bf16 v[12:15], v[150:153], v[206:209], v[12:15]
	v_mfma_f32_16x16x32_bf16 v[8:11], v[158:161], v[206:209], v[8:11]
	v_mfma_f32_16x16x32_bf16 v[60:63], v[154:157], v[186:189], v[60:63]
	v_mfma_f32_16x16x32_bf16 v[56:59], v[162:165], v[186:189], v[56:59]
	v_mfma_f32_16x16x32_bf16 v[44:47], v[154:157], v[194:197], v[44:47]
	v_mfma_f32_16x16x32_bf16 v[40:43], v[162:165], v[194:197], v[40:43]
	v_mfma_f32_16x16x32_bf16 v[28:31], v[154:157], v[202:205], v[28:31]
	v_mfma_f32_16x16x32_bf16 v[24:27], v[162:165], v[202:205], v[24:27]
	v_mfma_f32_16x16x32_bf16 v[12:15], v[154:157], v[210:213], v[12:15]
	v_mfma_f32_16x16x32_bf16 v[8:11], v[162:165], v[210:213], v[8:11]
	s_setprio 0
	s_setprio 1
	v_mfma_f32_16x16x32_bf16 v[52:55], v[166:169], v[182:185], v[52:55]
	v_mfma_f32_16x16x32_bf16 v[48:51], v[174:177], v[182:185], v[48:51]
	v_mfma_f32_16x16x32_bf16 v[36:39], v[166:169], v[190:193], v[36:39]
	v_mfma_f32_16x16x32_bf16 v[32:35], v[174:177], v[190:193], v[32:35]
	v_mfma_f32_16x16x32_bf16 v[20:23], v[166:169], v[198:201], v[20:23]
	v_mfma_f32_16x16x32_bf16 v[16:19], v[174:177], v[198:201], v[16:19]
	v_mfma_f32_16x16x32_bf16 v[4:7], v[166:169], v[206:209], v[4:7]
	v_mfma_f32_16x16x32_bf16 v[0:3], v[174:177], v[206:209], v[0:3]
	v_mfma_f32_16x16x32_bf16 v[52:55], v[170:173], v[186:189], v[52:55]
	v_mfma_f32_16x16x32_bf16 v[48:51], v[178:181], v[186:189], v[48:51]
	v_mfma_f32_16x16x32_bf16 v[36:39], v[170:173], v[194:197], v[36:39]
	v_mfma_f32_16x16x32_bf16 v[32:35], v[178:181], v[194:197], v[32:35]
	v_mfma_f32_16x16x32_bf16 v[20:23], v[170:173], v[202:205], v[20:23]
	v_mfma_f32_16x16x32_bf16 v[16:19], v[178:181], v[202:205], v[16:19]
	v_mfma_f32_16x16x32_bf16 v[4:7], v[170:173], v[210:213], v[4:7]
	v_mfma_f32_16x16x32_bf16 v[0:3], v[178:181], v[210:213], v[0:3]
	s_setprio 0
	s_barrier
	s_add_i32 s34, s34, 2
	s_add_u32 s8, s8, 0x100
	s_addc_u32 s9, s9, 0
	s_add_u32 vcc_lo, vcc_lo, 0x100
	s_addc_u32 vcc_hi, vcc_hi, 0
	s_cmp_gt_u32 s34, 29
	s_cbranch_scc0 .LBB0_704
	s_and_b64 vcc, exec, s[4:5]
	s_cbranch_vccz .LBB0_707
	s_barrier

; #define PG8_STAGE(bufoff, gbase, voff) do { _Pragma("unroll") for (int _i = 0; _i < 2; ++_i) \
;         __builtin_amdgcn_global_load_lds((const unsigned*)((const char*)(gbase) + (voff)[_i]), (PG8_LAS unsigned*)(lds + (bufoff) + ldsw + _i * 8192), 16, 0, 0); } while (0)
; #define PG8_LDA(dst, b, h) do { _Pragma("unroll") for (int m = 0; m < 4; ++m) _Pragma("unroll") for (int k = 0; k < 2; ++k) dst[m][k] = *(const PG8_LAS bf16x8*)(lds + PG8_SA(b, h) + aoff + m * 2048 + k * 1024); } while (0)
; #define PG8_LDB(dst, b, h) do { _Pragma("unroll") for (int n = 0; n < 2; ++n) _Pragma("unroll") for (int k = 0; k < 2; ++k) dst[n][k] = *(const PG8_LAS bf16x8*)(lds + PG8_SB(b, h) + boff + n * 2048 + k * 1024); } while (0)
; #define PG8_MMA(ai, bj, At, Bt) do { __builtin_amdgcn_s_setprio(1); _Pragma("unroll") for (int m = 0; m < 4; ++m) _Pragma("unroll") for (int n = 0; n < 2; ++n) _Pragma("unroll") for (int k = 0; k < 2; ++k) \
;         acc[ai][bj][m][n] = __builtin_amdgcn_mfma_f32_16x16x32_bf16(Bt[n][k], At[m][k], acc[ai][bj][m][n], 0, 0, 0); __builtin_amdgcn_s_setprio(0); } while (0)
; #define PG8_WAIT_V(n) asm volatile("s_waitcnt vmcnt(" #n ")" ::: "memory")
; #define PG8_WAIT_L(n) asm volatile("s_waitcnt lgkmcnt(" #n ")" ::: "memory")
; template <class Epi, class Sched, bool ALIGN_EPI = false, bool SP2 = false>
; __device__ __forceinline__ void gemm_phase(PG8_LAS unsigned char* lds, const Gemm g, const Sched& S, const Epi& E) {
;     ...
;             const bool last = (t == nt - 2);
;             const char* a1 = cA + (size_t)(t + 1) * kstep;
;             const char* a2 = last ? nA : cA + (size_t)(t + 2) * kstep; const char* b2 = last ? nB : cB + (size_t)(t + 2) * kstep;
;             const char* a3 = a2 + kstep; const char* b3 = b2 + kstep;
;             if (last && has_next) S.a_ready(nxt);
;             if constexpr (SP2) {
;             PG8_LDB(B0, 0, 0); PG8_LDB(B1, 0, 1); PG8_SCHED; PG8_LDA(At, 0, 0); PG8_STAGE(PG8_SA(1, 1), a1 + hstep, voffA);
;             PG8_WAIT_V(8); PG8_WAIT_L(0); PG8_BAR; PG8_MMA(0, 0, At, B0); PG8_MMA(0, 1, At, B1); PG8_BAR; PG8_SCHED;
;             PG8_LDA(At, 0, 1); PG8_STAGE(PG8_SB(0, 0), b2, voffB); PG8_STAGE(PG8_SB(0, 1), b2 + hstep, voffB); PG8_STAGE(PG8_SA(0, 0), a2, voffA);
;             PG8_WAIT_V(8); PG8_WAIT_L(0); PG8_BAR; PG8_MMA(1, 0, At, B0); PG8_MMA(1, 1, At, B1); PG8_BAR; PG8_SCHED;
.LBB0_783:
	s_add_u32 vcc_lo, s38, 0x100
	s_addc_u32 vcc_hi, s39, 0
	s_add_i32 s54, 0, 0x10000
	s_cmpk_eq_i32 s35, 0x7c
	s_cselect_b32 s15, s1, vcc_hi
	s_cselect_b32 s14, s9, vcc_lo
	v_add_u32_e32 v140, s54, v143
	s_cselect_b32 s5, s7, s34
	s_cselect_b32 s4, s30, s31
	s_add_i32 s80, 0, 0x14000
	ds_read_b128 v[136:139], v140
	ds_read_b128 v[148:151], v140 offset:1024
	ds_read_b128 v[152:155], v140 offset:2048
	ds_read_b128 v[156:159], v140 offset:3072
	v_add_u32_e32 v140, s80, v143
	ds_read_b128 v[160:163], v140
	ds_read_b128 v[164:167], v140 offset:1024
	ds_read_b128 v[168:171], v140 offset:2048
	ds_read_b128 v[172:175], v140 offset:3072
	v_lshl_add_u64 v[140:141], s[38:39], 0, v[132:133]
	s_add_i32 m0, s91, 0xc000
	ds_read_b128 v[176:179], v146
	ds_read_b128 v[180:183], v146 offset:1024
	ds_read_b128 v[184:187], v146 offset:2048
	ds_read_b128 v[188:191], v146 offset:3072
	ds_read_b128 v[192:195], v146 offset:4096
	ds_read_b128 v[196:199], v146 offset:5120
	ds_read_b128 v[200:203], v146 offset:6144
	ds_read_b128 v[204:207], v146 offset:7168
	global_load_lds_dwordx4 v[140:141], off
	v_lshl_add_u64 v[140:141], s[38:39], 0, v[134:135]
	s_add_i32 m0, s91, 0xe000
	s_nop 0
	global_load_lds_dwordx4 v[140:141], off
	s_waitcnt vmcnt(8)
	s_waitcnt lgkmcnt(0)
	s_barrier
	s_setprio 1
	s_waitcnt lgkmcnt(0)
	v_mfma_f32_16x16x32_bf16 v[124:127], v[136:139], v[176:179], v[124:127]
	v_mfma_f32_16x16x32_bf16 v[120:123], v[152:155], v[176:179], v[120:123]
	v_mfma_f32_16x16x32_bf16 v[108:111], v[136:139], v[184:187], v[108:111]
	v_mfma_f32_16x16x32_bf16 v[104:107], v[152:155], v[184:187], v[104:107]
	v_mfma_f32_16x16x32_bf16 v[92:95], v[136:139], v[192:195], v[92:95]
	v_mfma_f32_16x16x32_bf16 v[88:91], v[152:155], v[192:195], v[88:91]
	v_mfma_f32_16x16x32_bf16 v[76:79], v[136:139], v[200:203], v[76:79]
	v_mfma_f32_16x16x32_bf16 v[72:75], v[152:155], v[200:203], v[72:75]
	v_mfma_f32_16x16x32_bf16 v[124:127], v[148:151], v[180:183], v[124:127]
	v_mfma_f32_16x16x32_bf16 v[120:123], v[156:159], v[180:183], v[120:123]
	v_mfma_f32_16x16x32_bf16 v[108:111], v[148:151], v[188:191], v[108:111]
	v_mfma_f32_16x16x32_bf16 v[104:107], v[156:159], v[188:191], v[104:107]
	v_mfma_f32_16x16x32_bf16 v[92:95], v[148:151], v[196:199], v[92:95]
	v_mfma_f32_16x16x32_bf16 v[88:91], v[156:159], v[196:199], v[88:91]
	v_mfma_f32_16x16x32_bf16 v[76:79], v[148:151], v[204:207], v[76:79]
	v_mfma_f32_16x16x32_bf16 v[72:75], v[156:159], v[204:207], v[72:75]
	s_setprio 0
	s_setprio 1
	v_mfma_f32_16x16x32_bf16 v[116:119], v[160:163], v[176:179], v[116:119]
	v_mfma_f32_16x16x32_bf16 v[112:115], v[168:171], v[176:179], v[112:115]
	v_mfma_f32_16x16x32_bf16 v[100:103], v[160:163], v[184:187], v[100:103]
	v_mfma_f32_16x16x32_bf16 v[96:99], v[168:171], v[184:187], v[96:99]
	v_mfma_f32_16x16x32_bf16 v[84:87], v[160:163], v[192:195], v[84:87]
	v_mfma_f32_16x16x32_bf16 v[80:83], v[168:171], v[192:195], v[80:83]
	v_mfma_f32_16x16x32_bf16 v[68:71], v[160:163], v[200:203], v[68:71]
	v_mfma_f32_16x16x32_bf16 v[64:67], v[168:171], v[200:203], v[64:67]
	v_mfma_f32_16x16x32_bf16 v[116:119], v[164:167], v[180:183], v[116:119]
	v_mfma_f32_16x16x32_bf16 v[112:115], v[172:175], v[180:183], v[112:115]
	v_mfma_f32_16x16x32_bf16 v[100:103], v[164:167], v[188:191], v[100:103]
	v_mfma_f32_16x16x32_bf16 v[96:99], v[172:175], v[188:191], v[96:99]
	v_mfma_f32_16x16x32_bf16 v[84:87], v[164:167], v[196:199], v[84:87]
	v_mfma_f32_16x16x32_bf16 v[80:83], v[172:175], v[196:199], v[80:83]
	v_mfma_f32_16x16x32_bf16 v[68:71], v[164:167], v[204:207], v[68:71]
	v_mfma_f32_16x16x32_bf16 v[64:67], v[172:175], v[204:207], v[64:67]
	s_setprio 0
	s_barrier
	s_add_i32 s38, s54, s23
	v_lshl_add_u64 v[140:141], s[4:5], 0, v[128:129]
	s_mov_b32 m0, s38
	ds_read_b128 v[176:179], v146 offset:16384
	ds_read_b128 v[180:183], v146 offset:17408
	ds_read_b128 v[184:187], v146 offset:18432
	ds_read_b128 v[188:191], v146 offset:19456
	ds_read_b128 v[192:195], v146 offset:20480
	ds_read_b128 v[196:199], v146 offset:21504
	ds_read_b128 v[200:203], v146 offset:22528
	ds_read_b128 v[204:207], v146 offset:23552
	global_load_lds_dwordx4 v[140:141], off
	s_add_i32 m0, s38, 0x2000
	s_add_u32 s38, s4, 0x200000
	v_lshl_add_u64 v[208:209], s[4:5], 0, v[130:131]
	s_addc_u32 s39, s5, 0
	s_add_i32 s54, s80, s23
	global_load_lds_dwordx4 v[208:209], off
	v_lshl_add_u64 v[210:211], s[38:39], 0, v[128:129]
	s_mov_b32 m0, s54
	v_lshl_add_u64 v[212:213], s[14:15], 0, v[130:131]
	global_load_lds_dwordx4 v[210:211], off
	v_lshl_add_u64 v[210:211], s[38:39], 0, v[130:131]
	s_add_i32 m0, s54, 0x2000
	s_nop 0
	global_load_lds_dwordx4 v[210:211], off
	s_waitcnt vmcnt(6)
	s_waitcnt lgkmcnt(0)
	s_barrier
; #define PG8_STAGE(bufoff, gbase, voff) do { _Pragma("unroll") for (int _i = 0; _i < 2; ++_i) \
;         __builtin_amdgcn_global_load_lds((const unsigned*)((const char*)(gbase) + (voff)[_i]), (PG8_LAS unsigned*)(lds + (bufoff) + ldsw + _i * 8192), 16, 0, 0); } while (0)
; #define PG8_LDA(dst, b, h) do { _Pragma("unroll") for (int m = 0; m < 4; ++m) _Pragma("unroll") for (int k = 0; k < 2; ++k) dst[m][k] = *(const PG8_LAS bf16x8*)(lds + PG8_SA(b, h) + aoff + m * 2048 + k * 1024); } while (0)
; #define PG8_LDB(dst, b, h) do { _Pragma("unroll") for (int n = 0; n < 2; ++n) _Pragma("unroll") for (int k = 0; k < 2; ++k) dst[n][k] = *(const PG8_LAS bf16x8*)(lds + PG8_SB(b, h) + boff + n * 2048 + k * 1024); } while (0)
; #define PG8_MMA(ai, bj, At, Bt) do { __builtin_amdgcn_s_setprio(1); _Pragma("unroll") for (int m = 0; m < 4; ++m) _Pragma("unroll") for (int n = 0; n < 2; ++n) _Pragma("unroll") for (int k = 0; k < 2; ++k) \
;         acc[ai][bj][m][n] = __builtin_amdgcn_mfma_f32_16x16x32_bf16(Bt[n][k], At[m][k], acc[ai][bj][m][n], 0, 0, 0); __builtin_amdgcn_s_setprio(0); } while (0)
; #define PG8_WAIT_V(n) asm volatile("s_waitcnt vmcnt(" #n ")" ::: "memory")
; #define PG8_WAIT_L(n) asm volatile("s_waitcnt lgkmcnt(" #n ")" ::: "memory")
; #define PG8_BAR __builtin_amdgcn_s_barrier()
; #define PG8_SCHED __builtin_amdgcn_sched_barrier(0)
; template <class Epi, class Sched, bool ALIGN_EPI = false, bool SP2 = false>
; __device__ __forceinline__ void gemm_phase(PG8_LAS unsigned char* lds, const Gemm g, const Sched& S, const Epi& E) {
;     ...
;             PG8_WAIT_V(8); PG8_WAIT_L(0); PG8_BAR; PG8_MMA(1, 0, At, B0); PG8_MMA(1, 1, At, B1); PG8_BAR; PG8_SCHED;
;             PG8_LDB(B0, 1, 0); PG8_LDB(B1, 1, 1); PG8_SCHED; PG8_LDA(At, 1, 0); PG8_STAGE(PG8_SA(0, 1), a2 + hstep, voffA);
;             PG8_WAIT_V(8); PG8_WAIT_L(0); PG8_BAR; PG8_MMA(0, 0, At, B0); PG8_MMA(0, 1, At, B1); PG8_BAR; PG8_SCHED;
	s_setprio 1
	s_waitcnt lgkmcnt(0)
	v_mfma_f32_16x16x32_bf16 v[60:63], v[136:139], v[176:179], v[60:63]
	v_mfma_f32_16x16x32_bf16 v[56:59], v[152:155], v[176:179], v[56:59]
	v_mfma_f32_16x16x32_bf16 v[44:47], v[136:139], v[184:187], v[44:47]
	v_mfma_f32_16x16x32_bf16 v[40:43], v[152:155], v[184:187], v[40:43]
	v_mfma_f32_16x16x32_bf16 v[28:31], v[136:139], v[192:195], v[28:31]
	v_mfma_f32_16x16x32_bf16 v[24:27], v[152:155], v[192:195], v[24:27]
	v_mfma_f32_16x16x32_bf16 v[12:15], v[136:139], v[200:203], v[12:15]
	v_mfma_f32_16x16x32_bf16 v[8:11], v[152:155], v[200:203], v[8:11]
	v_mfma_f32_16x16x32_bf16 v[60:63], v[148:151], v[180:183], v[60:63]
	v_mfma_f32_16x16x32_bf16 v[56:59], v[156:159], v[180:183], v[56:59]
	v_mfma_f32_16x16x32_bf16 v[44:47], v[148:151], v[188:191], v[44:47]
	v_mfma_f32_16x16x32_bf16 v[40:43], v[156:159], v[188:191], v[40:43]
	v_mfma_f32_16x16x32_bf16 v[28:31], v[148:151], v[196:199], v[28:31]
	v_mfma_f32_16x16x32_bf16 v[24:27], v[156:159], v[196:199], v[24:27]
	v_mfma_f32_16x16x32_bf16 v[12:15], v[148:151], v[204:207], v[12:15]
	v_mfma_f32_16x16x32_bf16 v[8:11], v[156:159], v[204:207], v[8:11]
	s_setprio 0
	s_setprio 1
	v_mfma_f32_16x16x32_bf16 v[52:55], v[160:163], v[176:179], v[52:55]
	v_mfma_f32_16x16x32_bf16 v[48:51], v[168:171], v[176:179], v[48:51]
	v_mfma_f32_16x16x32_bf16 v[36:39], v[160:163], v[184:187], v[36:39]
	v_mfma_f32_16x16x32_bf16 v[32:35], v[168:171], v[184:187], v[32:35]
	v_mfma_f32_16x16x32_bf16 v[20:23], v[160:163], v[192:195], v[20:23]
	v_mfma_f32_16x16x32_bf16 v[16:19], v[168:171], v[192:195], v[16:19]
	v_mfma_f32_16x16x32_bf16 v[4:7], v[160:163], v[200:203], v[4:7]
	v_mfma_f32_16x16x32_bf16 v[0:3], v[168:171], v[200:203], v[0:3]
	v_mfma_f32_16x16x32_bf16 v[52:55], v[164:167], v[180:183], v[52:55]
	v_mfma_f32_16x16x32_bf16 v[48:51], v[172:175], v[180:183], v[48:51]
	v_mfma_f32_16x16x32_bf16 v[36:39], v[164:167], v[188:191], v[36:39]
	v_mfma_f32_16x16x32_bf16 v[32:35], v[172:175], v[188:191], v[32:35]
	v_mfma_f32_16x16x32_bf16 v[20:23], v[164:167], v[196:199], v[20:23]
	v_mfma_f32_16x16x32_bf16 v[16:19], v[172:175], v[196:199], v[16:19]
	v_mfma_f32_16x16x32_bf16 v[4:7], v[164:167], v[204:207], v[4:7]
	v_mfma_f32_16x16x32_bf16 v[0:3], v[172:175], v[204:207], v[0:3]
	s_setprio 0
	s_barrier
	v_lshl_add_u64 v[210:211], s[14:15], 0, v[128:129]
	s_mov_b32 m0, s91
	s_nop 0
	global_load_lds_dwordx4 v[210:211], off
	s_mov_b32 m0, s24
	s_nop 0
	global_load_lds_dwordx4 v[212:213], off
	s_add_i32 s38, 0, 0x18000
	v_add_u32_e32 v147, s38, v143
	s_add_i32 s39, 0, 0x1c000
	ds_read_b128 v[136:139], v147
	ds_read_b128 v[148:151], v147 offset:1024
	ds_read_b128 v[152:155], v147 offset:2048
	ds_read_b128 v[156:159], v147 offset:3072
	v_add_u32_e32 v147, s39, v143
	ds_read_b128 v[160:163], v147
	ds_read_b128 v[164:167], v147 offset:1024
	ds_read_b128 v[168:171], v147 offset:2048
	ds_read_b128 v[172:175], v147 offset:3072
	s_add_u32 s14, s14, 0x200000
	s_addc_u32 s15, s15, 0
	s_mov_b32 m0, s25
	v_lshl_add_u64 v[214:215], s[14:15], 0, v[128:129]
	ds_read_b128 v[176:179], v146 offset:32768
	ds_read_b128 v[180:183], v146 offset:33792
	ds_read_b128 v[184:187], v146 offset:34816
	ds_read_b128 v[188:191], v146 offset:35840
	ds_read_b128 v[192:195], v146 offset:36864
	ds_read_b128 v[196:199], v146 offset:37888
	ds_read_b128 v[200:203], v146 offset:38912
	ds_read_b128 v[204:207], v146 offset:39936
	global_load_lds_dwordx4 v[214:215], off
	v_lshl_add_u64 v[214:215], s[14:15], 0, v[130:131]
	s_mov_b32 m0, s26
	s_nop 0
	global_load_lds_dwordx4 v[214:215], off
	s_waitcnt vmcnt(8)
	s_waitcnt lgkmcnt(0)
	s_barrier
	s_setprio 1
	s_waitcnt lgkmcnt(0)
	v_mfma_f32_16x16x32_bf16 v[124:127], v[136:139], v[176:179], v[124:127]
	v_mfma_f32_16x16x32_bf16 v[120:123], v[152:155], v[176:179], v[120:123]
	v_mfma_f32_16x16x32_bf16 v[108:111], v[136:139], v[184:187], v[108:111]
	v_mfma_f32_16x16x32_bf16 v[104:107], v[152:155], v[184:187], v[104:107]
	v_mfma_f32_16x16x32_bf16 v[92:95], v[136:139], v[192:195], v[92:95]
	v_mfma_f32_16x16x32_bf16 v[88:91], v[152:155], v[192:195], v[88:91]
	v_mfma_f32_16x16x32_bf16 v[76:79], v[136:139], v[200:203], v[76:79]
	v_mfma_f32_16x16x32_bf16 v[72:75], v[152:155], v[200:203], v[72:75]
	v_mfma_f32_16x16x32_bf16 v[124:127], v[148:151], v[180:183], v[124:127]
	v_mfma_f32_16x16x32_bf16 v[120:123], v[156:159], v[180:183], v[120:123]
	v_mfma_f32_16x16x32_bf16 v[108:111], v[148:151], v[188:191], v[108:111]
	v_mfma_f32_16x16x32_bf16 v[104:107], v[156:159], v[188:191], v[104:107]
	v_mfma_f32_16x16x32_bf16 v[92:95], v[148:151], v[196:199], v[92:95]
	v_mfma_f32_16x16x32_bf16 v[88:91], v[156:159], v[196:199], v[88:91]
	v_mfma_f32_16x16x32_bf16 v[76:79], v[148:151], v[204:207], v[76:79]
	v_mfma_f32_16x16x32_bf16 v[72:75], v[156:159], v[204:207], v[72:75]
	s_setprio 0
	s_setprio 1
	v_mfma_f32_16x16x32_bf16 v[116:119], v[160:163], v[176:179], v[116:119]
	v_mfma_f32_16x16x32_bf16 v[112:115], v[168:171], v[176:179], v[112:115]
	v_mfma_f32_16x16x32_bf16 v[100:103], v[160:163], v[184:187], v[100:103]
	v_mfma_f32_16x16x32_bf16 v[96:99], v[168:171], v[184:187], v[96:99]
	v_mfma_f32_16x16x32_bf16 v[84:87], v[160:163], v[192:195], v[84:87]
	v_mfma_f32_16x16x32_bf16 v[80:83], v[168:171], v[192:195], v[80:83]
	v_mfma_f32_16x16x32_bf16 v[68:71], v[160:163], v[200:203], v[68:71]
	v_mfma_f32_16x16x32_bf16 v[64:67], v[168:171], v[200:203], v[64:67]
	v_mfma_f32_16x16x32_bf16 v[116:119], v[164:167], v[180:183], v[116:119]
	v_mfma_f32_16x16x32_bf16 v[112:115], v[172:175], v[180:183], v[112:115]
	v_mfma_f32_16x16x32_bf16 v[100:103], v[164:167], v[188:191], v[100:103]
	v_mfma_f32_16x16x32_bf16 v[96:99], v[172:175], v[188:191], v[96:99]
	v_mfma_f32_16x16x32_bf16 v[84:87], v[164:167], v[196:199], v[84:87]
	v_mfma_f32_16x16x32_bf16 v[80:83], v[172:175], v[196:199], v[80:83]
	v_mfma_f32_16x16x32_bf16 v[68:71], v[164:167], v[204:207], v[68:71]
	v_mfma_f32_16x16x32_bf16 v[64:67], v[172:175], v[204:207], v[64:67]
	s_setprio 0
	s_barrier
; #define PG8_STAGE(bufoff, gbase, voff) do { _Pragma("unroll") for (int _i = 0; _i < 2; ++_i) \
;         __builtin_amdgcn_global_load_lds((const unsigned*)((const char*)(gbase) + (voff)[_i]), (PG8_LAS unsigned*)(lds + (bufoff) + ldsw + _i * 8192), 16, 0, 0); } while (0)
; #define PG8_LDA(dst, b, h) do { _Pragma("unroll") for (int m = 0; m < 4; ++m) _Pragma("unroll") for (int k = 0; k < 2; ++k) dst[m][k] = *(const PG8_LAS bf16x8*)(lds + PG8_SA(b, h) + aoff + m * 2048 + k * 1024); } while (0)
; #define PG8_MMA(ai, bj, At, Bt) do { __builtin_amdgcn_s_setprio(1); _Pragma("unroll") for (int m = 0; m < 4; ++m) _Pragma("unroll") for (int n = 0; n < 2; ++n) _Pragma("unroll") for (int k = 0; k < 2; ++k) \
;         acc[ai][bj][m][n] = __builtin_amdgcn_mfma_f32_16x16x32_bf16(Bt[n][k], At[m][k], acc[ai][bj][m][n], 0, 0, 0); __builtin_amdgcn_s_setprio(0); } while (0)
; #define PG8_WAIT_V(n) asm volatile("s_waitcnt vmcnt(" #n ")" ::: "memory")
; #define PG8_WAIT_L(n) asm volatile("s_waitcnt lgkmcnt(" #n ")" ::: "memory")
; #define PG8_BAR __builtin_amdgcn_s_barrier()
; #define PG8_SCHED __builtin_amdgcn_sched_barrier(0)
; template <class Epi, class Sched, bool ALIGN_EPI = false, bool SP2 = false>
; __device__ __forceinline__ void gemm_phase(PG8_LAS unsigned char* lds, const Gemm g, const Sched& S, const Epi& E) {
;     ...
;             PG8_LDA(At, 1, 1); PG8_STAGE(PG8_SB(1, 0), b3, voffB); PG8_STAGE(PG8_SB(1, 1), b3 + hstep, voffB); PG8_STAGE(PG8_SA(1, 0), a3, voffA);
;             PG8_WAIT_V(8); PG8_WAIT_L(0); PG8_BAR; PG8_MMA(1, 0, At, B0); PG8_MMA(1, 1, At, B1); PG8_BAR; PG8_SCHED;
	s_add_i32 s14, s38, s23
	v_lshl_add_u64 v[140:141], v[140:141], 0, s[84:85]
	s_mov_b32 m0, s14
	ds_read_b128 v[176:179], v146 offset:49152
	ds_read_b128 v[180:183], v146 offset:50176
	ds_read_b128 v[184:187], v146 offset:51200
	ds_read_b128 v[188:191], v146 offset:52224
	ds_read_b128 v[192:195], v146 offset:53248
	ds_read_b128 v[196:199], v146 offset:54272
	ds_read_b128 v[200:203], v146 offset:55296
	ds_read_b128 v[204:207], v146 offset:56320
	global_load_lds_dwordx4 v[140:141], off
	s_add_i32 m0, s14, 0x2000
	s_add_u32 s4, s4, 0x200080
	v_lshl_add_u64 v[140:141], v[208:209], 0, s[84:85]
	s_addc_u32 s5, s5, 0
	s_add_i32 s14, s39, s23
	global_load_lds_dwordx4 v[140:141], off
	v_lshl_add_u64 v[140:141], s[4:5], 0, v[128:129]
	s_mov_b32 m0, s14
	s_nop 0
	global_load_lds_dwordx4 v[140:141], off
	v_lshl_add_u64 v[140:141], s[4:5], 0, v[130:131]
	s_add_i32 m0, s14, 0x2000
	s_nop 0
	global_load_lds_dwordx4 v[140:141], off
	v_lshl_add_u64 v[140:141], v[210:211], 0, s[84:85]
	s_mov_b32 m0, s20
	s_nop 0
	global_load_lds_dwordx4 v[140:141], off
	v_lshl_add_u64 v[140:141], v[212:213], 0, s[84:85]
	s_mov_b32 m0, s27
	s_nop 0
	global_load_lds_dwordx4 v[140:141], off
	s_waitcnt vmcnt(8)
	s_waitcnt lgkmcnt(0)
	s_barrier
	s_setprio 1
	s_waitcnt lgkmcnt(0)
	v_mfma_f32_16x16x32_bf16 v[60:63], v[136:139], v[176:179], v[60:63]
	v_mfma_f32_16x16x32_bf16 v[56:59], v[152:155], v[176:179], v[56:59]
	v_mfma_f32_16x16x32_bf16 v[44:47], v[136:139], v[184:187], v[44:47]
	v_mfma_f32_16x16x32_bf16 v[40:43], v[152:155], v[184:187], v[40:43]
	v_mfma_f32_16x16x32_bf16 v[28:31], v[136:139], v[192:195], v[28:31]
	v_mfma_f32_16x16x32_bf16 v[24:27], v[152:155], v[192:195], v[24:27]
	v_mfma_f32_16x16x32_bf16 v[12:15], v[136:139], v[200:203], v[12:15]
	v_mfma_f32_16x16x32_bf16 v[8:11], v[152:155], v[200:203], v[8:11]
	v_mfma_f32_16x16x32_bf16 v[60:63], v[148:151], v[180:183], v[60:63]
	v_mfma_f32_16x16x32_bf16 v[56:59], v[156:159], v[180:183], v[56:59]
	v_mfma_f32_16x16x32_bf16 v[44:47], v[148:151], v[188:191], v[44:47]
	v_mfma_f32_16x16x32_bf16 v[40:43], v[156:159], v[188:191], v[40:43]
	v_mfma_f32_16x16x32_bf16 v[28:31], v[148:151], v[196:199], v[28:31]
	v_mfma_f32_16x16x32_bf16 v[24:27], v[156:159], v[196:199], v[24:27]
	v_mfma_f32_16x16x32_bf16 v[12:15], v[148:151], v[204:207], v[12:15]
	v_mfma_f32_16x16x32_bf16 v[8:11], v[156:159], v[204:207], v[8:11]
	s_setprio 0
	s_setprio 1
	v_mfma_f32_16x16x32_bf16 v[52:55], v[160:163], v[176:179], v[52:55]
	v_mfma_f32_16x16x32_bf16 v[48:51], v[168:171], v[176:179], v[48:51]
	v_mfma_f32_16x16x32_bf16 v[36:39], v[160:163], v[184:187], v[36:39]
	v_mfma_f32_16x16x32_bf16 v[32:35], v[168:171], v[184:187], v[32:35]
	v_mfma_f32_16x16x32_bf16 v[20:23], v[160:163], v[192:195], v[20:23]
	v_mfma_f32_16x16x32_bf16 v[16:19], v[168:171], v[192:195], v[16:19]
	v_mfma_f32_16x16x32_bf16 v[4:7], v[160:163], v[200:203], v[4:7]
	v_mfma_f32_16x16x32_bf16 v[0:3], v[168:171], v[200:203], v[0:3]
	v_mfma_f32_16x16x32_bf16 v[52:55], v[164:167], v[180:183], v[52:55]
	v_mfma_f32_16x16x32_bf16 v[48:51], v[172:175], v[180:183], v[48:51]
	v_mfma_f32_16x16x32_bf16 v[36:39], v[164:167], v[188:191], v[36:39]
	v_mfma_f32_16x16x32_bf16 v[32:35], v[172:175], v[188:191], v[32:35]
	v_mfma_f32_16x16x32_bf16 v[20:23], v[164:167], v[196:199], v[20:23]
	v_mfma_f32_16x16x32_bf16 v[16:19], v[172:175], v[196:199], v[16:19]
	v_mfma_f32_16x16x32_bf16 v[4:7], v[164:167], v[204:207], v[4:7]
	v_mfma_f32_16x16x32_bf16 v[0:3], v[172:175], v[204:207], v[0:3]
	s_setprio 0
	s_barrier
	s_add_i32 s35, s35, 2
	s_add_u32 s31, s31, 0x100
	s_addc_u32 s34, s34, 0
	s_cmpk_gt_u32 s35, 0x7d
	s_mov_b64 s[38:39], vcc
	s_cbranch_scc0 .LBB0_783
	s_and_b64 vcc, exec, s[96:97]
	s_cbranch_vccz .LBB0_786
	s_barrier
